# attention K tile LDS swizzle widened to 16 slots (row&15) so the ds_read_b128 K-fragment reads are bank-conflict free
# speedup vs baseline: 1.0300x; 1.0013x over previous
.LBB0_891:
	s_cmpk_gt_i32 s67, 0xff
	s_mov_b64 s[40:41], -1
	s_cbranch_scc0 .LBB0_896
	s_add_i32 s2, s67, 0xffffff00
	s_lshr_b32 s72, s2, 3
	s_and_b32 s2, s67, 7
	s_mul_i32 s4, s72, 0xc0000
	s_add_u32 s4, s4, 0x3000000
	s_add_u32 s3, s39, s4
	s_addc_u32 s4, s52, 0
	s_lshl_b32 s5, s2, 8
	s_add_u32 s40, s3, s5
	s_addc_u32 s41, s4, 0
	s_lshl_b32 s3, s67, 14
	s_and_b32 s3, s3, 0x10000
	s_lshl_b64 s[4:5], s[72:73], 17
	s_waitcnt vmcnt(2)
	v_mov_b32_e32 v58, v204
	s_or_b32 s3, s4, s3
	s_add_u32 s44, s53, s3
	v_ashrrev_i32_e32 v16, 4, v58
	v_lshlrev_b32_e32 v22, 3, v58
	v_add_u32_e32 v18, 32, v16
	s_addc_u32 s45, s54, s5
	s_waitcnt vmcnt(0)
	v_and_b32_e32 v0, 0x78, v22
	v_ashrrev_i32_e32 v17, 31, v16
	v_ashrrev_i32_e32 v19, 31, v18
	s_add_u32 s48, s55, s3
	v_lshlrev_b32_e32 v23, 1, v0
	s_waitcnt vmcnt(0)
	v_lshlrev_b64 v[32:33], 8, v[16:17]
	v_lshlrev_b64 v[8:9], 8, v[18:19]
	s_addc_u32 s49, s60, s5
	v_or_b32_e32 v32, v32, v23
	v_or_b32_e32 v8, v8, v23
	v_lshl_add_u64 v[0:1], s[48:49], 0, v[32:33]
	v_lshl_add_u64 v[4:5], s[48:49], 0, v[8:9]
	v_lshl_add_u64 v[10:11], s[44:45], 0, v[32:33]
	v_lshl_add_u64 v[12:13], s[44:45], 0, v[8:9]
	global_load_dwordx4 v[0:3], v[0:1], off
	s_nop 0
	global_load_dwordx4 v[4:7], v[4:5], off
	s_nop 0
	global_load_dwordx4 v[8:11], v[10:11], off
	s_nop 0
	global_load_dwordx4 v[12:15], v[12:13], off
	v_ashrrev_i32_e32 v186, 1, v58
	s_movk_i32 s3, 0xffe0
	v_bfi_b32 v20, s3, v186, v58
	v_ashrrev_i32_e32 v21, 31, v20
	v_bfe_u32 v162, v58, 5, 1
	v_mul_u32_u24_e32 v20, 0xc00, v20
	v_lshl_add_u64 v[20:21], s[40:41], 0, v[20:21]
	v_lshlrev_b32_e32 v96, 4, v162
	v_lshl_add_u64 v[20:21], v[20:21], 0, v[96:97]
	global_load_dwordx4 v[114:117], v[20:21], off
	global_load_dwordx4 v[110:113], v[20:21], off offset:32
	global_load_dwordx4 v[122:125], v[20:21], off offset:64
	global_load_dwordx4 v[126:129], v[20:21], off offset:96
	global_load_dwordx4 v[118:121], v[20:21], off offset:128
	global_load_dwordx4 v[106:109], v[20:21], off offset:160
	global_load_dwordx4 v[102:105], v[20:21], off offset:192
	global_load_dwordx4 v[98:101], v[20:21], off offset:224
	v_and_b32_e32 v19, 0xfffff0, v16
	v_lshlrev_b32_e32 v24, 1, v16
	v_lshrrev_b32_e32 v25, 1, v16
	v_and_b32_e32 v26, 3, v16
	v_and_or_b32 v19, v24, 8, v19
	v_and_or_b32 v24, v25, 4, v26
	v_and_b32_e32 v25, 0xfffff0, v18
	v_lshlrev_b32_e32 v26, 1, v18
	v_and_b32_e32 v17, 0xf0, v58
	v_bfe_u32 v22, v22, 5, 2
	v_lshlrev_b32_e32 v16, 8, v16
	v_lshlrev_b32_e32 v18, 8, v18
	v_lshrrev_b32_e32 v19, 1, v19
	v_and_or_b32 v25, v26, 8, v25
	v_bitop3_b32 v16, v23, v16, v17 bitop3:0xde
	v_bitop3_b32 v17, v23, v18, v17 bitop3:0xde
	v_or_b32_e32 v18, v19, v22
	v_lshrrev_b32_e32 v19, 1, v25
	v_lshlrev_b32_e32 v24, 6, v24
	v_and_b32_e32 v27, 48, v23
	v_add_u32_e32 v182, 0, v16
	v_add_u32_e32 v183, 0, v17
	v_lshlrev_b32_e32 v16, 9, v18
	v_or_b32_e32 v17, v19, v22
	v_and_b32_e32 v163, 31, v58
	v_lshlrev_b32_e32 v59, 4, v58
	v_or3_b32 v16, v16, v24, v27
	v_lshlrev_b32_e32 v17, 9, v17
	v_lshlrev_b32_e32 v54, 8, v163
	v_and_b32_e32 v55, 0xf0, v59
	v_or3_b32 v17, v17, v24, v27
	v_add_u32_e32 v184, 0, v16
	v_add_u32_e32 v185, 0, v17
	s_waitcnt vmcnt(0)
	v_or_b32_e32 v20, 32, v96
	v_bitop3_b32 v20, v20, v54, v55 bitop3:0xde
	v_add_u32_e32 v176, 0, v20
	s_mov_b64 s[4:5], 0x4000
	v_lshl_add_u64 v[42:43], v[32:33], 0, s[4:5]
	s_mov_b64 s[4:5], 0x6000
	v_or_b32_e32 v56, 0xe0, v96
	v_lshl_add_u64 v[44:45], v[32:33], 0, s[4:5]
	v_lshl_add_u64 v[50:51], s[44:45], 0, v[42:43]
	v_lshl_add_u64 v[52:53], s[44:45], 0, v[44:45]
	v_lshl_add_u64 v[42:43], s[48:49], 0, v[42:43]
	v_lshl_add_u64 v[46:47], s[48:49], 0, v[44:45]
	s_waitcnt vmcnt(11)
	ds_write_b128 v184, v[0:3]
	s_waitcnt vmcnt(10)
	ds_write_b128 v185, v[4:7]
	s_waitcnt vmcnt(9)
	ds_write_b128 v182, v[8:11] offset:32768
	s_waitcnt vmcnt(8)
	ds_write_b128 v183, v[12:15] offset:32768
	s_load_dwordx2 s[100:101], s[88:89], 0x80
	v_lshlrev_b32_e32 v175, 5, v162
	s_waitcnt lgkmcnt(0)
	global_load_dwordx4 v[130:133], v175, s[100:101] offset:0
	global_load_dwordx4 v[134:137], v175, s[100:101] offset:16
	global_load_dwordx4 v[138:141], v175, s[100:101] offset:64
	global_load_dwordx4 v[142:145], v175, s[100:101] offset:80
	global_load_dwordx4 v[146:149], v175, s[100:101] offset:128
	global_load_dwordx4 v[150:153], v175, s[100:101] offset:144
	global_load_dwordx4 v[154:157], v175, s[100:101] offset:192
	global_load_dwordx4 v[158:161], v175, s[100:101] offset:208
	global_load_dwordx4 v[224:227], v175, s[100:101] offset:256
	global_load_dwordx4 v[228:231], v175, s[100:101] offset:272
	global_load_dwordx4 v[232:235], v175, s[100:101] offset:320
	global_load_dwordx4 v[236:239], v175, s[100:101] offset:336
	global_load_dwordx4 v[240:243], v175, s[100:101] offset:384
	global_load_dwordx4 v[244:247], v175, s[100:101] offset:400
	global_load_dwordx4 v[248:251], v175, s[100:101] offset:448
	global_load_dwordx4 v[164:167], v175, s[100:101] offset:464
	v_lshlrev_b32_e32 v24, 16, v114
	v_and_b32_e32 v25, 0xffff0000, v114
	v_lshlrev_b32_e32 v26, 16, v115
	v_and_b32_e32 v27, 0xffff0000, v115
	v_lshlrev_b32_e32 v28, 16, v116
	v_and_b32_e32 v29, 0xffff0000, v116
	v_lshlrev_b32_e32 v30, 16, v117
	v_and_b32_e32 v31, 0xffff0000, v117
	v_mul_f32_e32 v168, v24, v24
	v_fmac_f32_e32 v168, v25, v25
	v_fmac_f32_e32 v168, v26, v26
	v_fmac_f32_e32 v168, v27, v27
	v_fmac_f32_e32 v168, v28, v28
	v_fmac_f32_e32 v168, v29, v29
	v_fmac_f32_e32 v168, v30, v30
	v_fmac_f32_e32 v168, v31, v31
	v_lshlrev_b32_e32 v24, 16, v110
	v_and_b32_e32 v25, 0xffff0000, v110
	v_lshlrev_b32_e32 v26, 16, v111
	v_and_b32_e32 v27, 0xffff0000, v111
	v_lshlrev_b32_e32 v28, 16, v112
	v_and_b32_e32 v29, 0xffff0000, v112
	v_lshlrev_b32_e32 v30, 16, v113
	v_and_b32_e32 v31, 0xffff0000, v113
	v_fmac_f32_e32 v168, v24, v24
	v_fmac_f32_e32 v168, v25, v25
	v_fmac_f32_e32 v168, v26, v26
	v_fmac_f32_e32 v168, v27, v27
	v_fmac_f32_e32 v168, v28, v28
	v_fmac_f32_e32 v168, v29, v29
	v_fmac_f32_e32 v168, v30, v30
	v_fmac_f32_e32 v168, v31, v31
	v_lshlrev_b32_e32 v24, 16, v122
	v_and_b32_e32 v25, 0xffff0000, v122
	v_lshlrev_b32_e32 v26, 16, v123
	v_and_b32_e32 v27, 0xffff0000, v123
	v_lshlrev_b32_e32 v28, 16, v124
	v_and_b32_e32 v29, 0xffff0000, v124
	v_lshlrev_b32_e32 v30, 16, v125
	v_and_b32_e32 v31, 0xffff0000, v125
	v_fmac_f32_e32 v168, v24, v24
	v_fmac_f32_e32 v168, v25, v25
	v_fmac_f32_e32 v168, v26, v26
	v_fmac_f32_e32 v168, v27, v27
	v_fmac_f32_e32 v168, v28, v28
	v_fmac_f32_e32 v168, v29, v29
	v_fmac_f32_e32 v168, v30, v30
	v_fmac_f32_e32 v168, v31, v31
	v_lshlrev_b32_e32 v24, 16, v126
	v_and_b32_e32 v25, 0xffff0000, v126
	v_lshlrev_b32_e32 v26, 16, v127
	v_and_b32_e32 v27, 0xffff0000, v127
	v_lshlrev_b32_e32 v28, 16, v128
	v_and_b32_e32 v29, 0xffff0000, v128
	v_lshlrev_b32_e32 v30, 16, v129
	v_and_b32_e32 v31, 0xffff0000, v129
	v_fmac_f32_e32 v168, v24, v24
	v_fmac_f32_e32 v168, v25, v25
	v_fmac_f32_e32 v168, v26, v26
	v_fmac_f32_e32 v168, v27, v27
	v_fmac_f32_e32 v168, v28, v28
	v_fmac_f32_e32 v168, v29, v29
	v_fmac_f32_e32 v168, v30, v30
	v_fmac_f32_e32 v168, v31, v31
	v_lshlrev_b32_e32 v24, 16, v118
	v_and_b32_e32 v25, 0xffff0000, v118
	v_lshlrev_b32_e32 v26, 16, v119
	v_and_b32_e32 v27, 0xffff0000, v119
	v_lshlrev_b32_e32 v28, 16, v120
	v_and_b32_e32 v29, 0xffff0000, v120
	v_lshlrev_b32_e32 v30, 16, v121
	v_and_b32_e32 v31, 0xffff0000, v121
	v_fmac_f32_e32 v168, v24, v24
	v_fmac_f32_e32 v168, v25, v25
	v_fmac_f32_e32 v168, v26, v26
	v_fmac_f32_e32 v168, v27, v27
	v_fmac_f32_e32 v168, v28, v28
	v_fmac_f32_e32 v168, v29, v29
	v_fmac_f32_e32 v168, v30, v30
	v_fmac_f32_e32 v168, v31, v31
	v_lshlrev_b32_e32 v24, 16, v106
	v_and_b32_e32 v25, 0xffff0000, v106
	v_lshlrev_b32_e32 v26, 16, v107
	v_and_b32_e32 v27, 0xffff0000, v107
	v_lshlrev_b32_e32 v28, 16, v108
	v_and_b32_e32 v29, 0xffff0000, v108
	v_lshlrev_b32_e32 v30, 16, v109
	v_and_b32_e32 v31, 0xffff0000, v109
	v_fmac_f32_e32 v168, v24, v24
	v_fmac_f32_e32 v168, v25, v25
	v_fmac_f32_e32 v168, v26, v26
	v_fmac_f32_e32 v168, v27, v27
	v_fmac_f32_e32 v168, v28, v28
	v_fmac_f32_e32 v168, v29, v29
	v_fmac_f32_e32 v168, v30, v30
	v_fmac_f32_e32 v168, v31, v31
	v_lshlrev_b32_e32 v24, 16, v102
	v_and_b32_e32 v25, 0xffff0000, v102
	v_lshlrev_b32_e32 v26, 16, v103
	v_and_b32_e32 v27, 0xffff0000, v103
	v_lshlrev_b32_e32 v28, 16, v104
	v_and_b32_e32 v29, 0xffff0000, v104
	v_lshlrev_b32_e32 v30, 16, v105
	v_and_b32_e32 v31, 0xffff0000, v105
	v_fmac_f32_e32 v168, v24, v24
	v_fmac_f32_e32 v168, v25, v25
	v_fmac_f32_e32 v168, v26, v26
	v_fmac_f32_e32 v168, v27, v27
	v_fmac_f32_e32 v168, v28, v28
	v_fmac_f32_e32 v168, v29, v29
	v_fmac_f32_e32 v168, v30, v30
	v_fmac_f32_e32 v168, v31, v31
	v_lshlrev_b32_e32 v24, 16, v98
	v_and_b32_e32 v25, 0xffff0000, v98
	v_lshlrev_b32_e32 v26, 16, v99
	v_and_b32_e32 v27, 0xffff0000, v99
	v_lshlrev_b32_e32 v28, 16, v100
	v_and_b32_e32 v29, 0xffff0000, v100
	v_lshlrev_b32_e32 v30, 16, v101
	v_and_b32_e32 v31, 0xffff0000, v101
	v_fmac_f32_e32 v168, v24, v24
	v_fmac_f32_e32 v168, v25, v25
	v_fmac_f32_e32 v168, v26, v26
	v_fmac_f32_e32 v168, v27, v27
	v_fmac_f32_e32 v168, v28, v28
	v_fmac_f32_e32 v168, v29, v29
	v_fmac_f32_e32 v168, v30, v30
	v_fmac_f32_e32 v168, v31, v31
	v_mov_b32_e32 v170, v168
	s_nop 1
	v_permlane32_swap_b32_e32 v168, v170
	v_add_f32_e32 v168, v168, v170
	v_fmamk_f32 v168, v168, 0x3c000000, v207
	v_rsq_f32_e32 v169, v168
	s_nop 0
	v_mul_f32_e32 v170, v168, v169
	v_fma_f32 v170, -v170, v169, 1.0
	v_mul_f32_e32 v170, 0.5, v170
	v_fmac_f32_e32 v169, v169, v170
	s_waitcnt vmcnt(0)
	v_lshlrev_b32_e32 v24, 16, v114
	v_and_b32_e32 v25, 0xffff0000, v114
	v_lshlrev_b32_e32 v26, 16, v115
	v_and_b32_e32 v27, 0xffff0000, v115
	v_lshlrev_b32_e32 v28, 16, v116
	v_and_b32_e32 v29, 0xffff0000, v116
	v_lshlrev_b32_e32 v30, 16, v117
	v_and_b32_e32 v31, 0xffff0000, v117
	v_mul_f32_e32 v24, v24, v169
	v_mul_f32_e32 v25, v25, v169
	v_mul_f32_e32 v26, v26, v169
	v_mul_f32_e32 v27, v27, v169
	v_mul_f32_e32 v28, v28, v169
	v_mul_f32_e32 v29, v29, v169
	v_mul_f32_e32 v30, v30, v169
	v_mul_f32_e32 v31, v31, v169
	v_mul_f32_e32 v24, v24, v130
	v_mul_f32_e32 v25, v25, v131
	v_mul_f32_e32 v26, v26, v132
	v_mul_f32_e32 v27, v27, v133
	v_mul_f32_e32 v28, v28, v134
	v_mul_f32_e32 v29, v29, v135
	v_mul_f32_e32 v30, v30, v136
	v_mul_f32_e32 v31, v31, v137
	v_cvt_pk_bf16_f32 v114, v24, v25
	v_cvt_pk_bf16_f32 v115, v26, v27
	v_cvt_pk_bf16_f32 v116, v28, v29
	v_cvt_pk_bf16_f32 v117, v30, v31
	v_lshlrev_b32_e32 v24, 16, v110
	v_and_b32_e32 v25, 0xffff0000, v110
	v_lshlrev_b32_e32 v26, 16, v111
	v_and_b32_e32 v27, 0xffff0000, v111
	v_lshlrev_b32_e32 v28, 16, v112
	v_and_b32_e32 v29, 0xffff0000, v112
	v_lshlrev_b32_e32 v30, 16, v113
	v_and_b32_e32 v31, 0xffff0000, v113
	v_mul_f32_e32 v24, v24, v169
	v_mul_f32_e32 v25, v25, v169
	v_mul_f32_e32 v26, v26, v169
	v_mul_f32_e32 v27, v27, v169
	v_mul_f32_e32 v28, v28, v169
	v_mul_f32_e32 v29, v29, v169
	v_mul_f32_e32 v30, v30, v169
	v_mul_f32_e32 v31, v31, v169
	v_mul_f32_e32 v24, v24, v138
	v_mul_f32_e32 v25, v25, v139
	v_mul_f32_e32 v26, v26, v140
	v_mul_f32_e32 v27, v27, v141
	v_mul_f32_e32 v28, v28, v142
	v_mul_f32_e32 v29, v29, v143
	v_mul_f32_e32 v30, v30, v144
	v_mul_f32_e32 v31, v31, v145
	v_cvt_pk_bf16_f32 v110, v24, v25
	v_cvt_pk_bf16_f32 v111, v26, v27
	v_cvt_pk_bf16_f32 v112, v28, v29
	v_cvt_pk_bf16_f32 v113, v30, v31
	v_lshlrev_b32_e32 v24, 16, v122
	v_and_b32_e32 v25, 0xffff0000, v122
	v_lshlrev_b32_e32 v26, 16, v123
	v_and_b32_e32 v27, 0xffff0000, v123
	v_lshlrev_b32_e32 v28, 16, v124
	v_and_b32_e32 v29, 0xffff0000, v124
	v_lshlrev_b32_e32 v30, 16, v125
	v_and_b32_e32 v31, 0xffff0000, v125
	v_mul_f32_e32 v24, v24, v169
	v_mul_f32_e32 v25, v25, v169
	v_mul_f32_e32 v26, v26, v169
	v_mul_f32_e32 v27, v27, v169
	v_mul_f32_e32 v28, v28, v169
	v_mul_f32_e32 v29, v29, v169
	v_mul_f32_e32 v30, v30, v169
	v_mul_f32_e32 v31, v31, v169
	v_mul_f32_e32 v24, v24, v146
	v_mul_f32_e32 v25, v25, v147
	v_mul_f32_e32 v26, v26, v148
	v_mul_f32_e32 v27, v27, v149
	v_mul_f32_e32 v28, v28, v150
	v_mul_f32_e32 v29, v29, v151
	v_mul_f32_e32 v30, v30, v152
	v_mul_f32_e32 v31, v31, v153
	v_cvt_pk_bf16_f32 v122, v24, v25
	v_cvt_pk_bf16_f32 v123, v26, v27
	v_cvt_pk_bf16_f32 v124, v28, v29
	v_cvt_pk_bf16_f32 v125, v30, v31
	v_lshlrev_b32_e32 v24, 16, v126
	v_and_b32_e32 v25, 0xffff0000, v126
	v_lshlrev_b32_e32 v26, 16, v127
	v_and_b32_e32 v27, 0xffff0000, v127
	v_lshlrev_b32_e32 v28, 16, v128
	v_and_b32_e32 v29, 0xffff0000, v128
	v_lshlrev_b32_e32 v30, 16, v129
	v_and_b32_e32 v31, 0xffff0000, v129
	v_mul_f32_e32 v24, v24, v169
	v_mul_f32_e32 v25, v25, v169
	v_mul_f32_e32 v26, v26, v169
	v_mul_f32_e32 v27, v27, v169
	v_mul_f32_e32 v28, v28, v169
	v_mul_f32_e32 v29, v29, v169
	v_mul_f32_e32 v30, v30, v169
	v_mul_f32_e32 v31, v31, v169
	v_mul_f32_e32 v24, v24, v154
	v_mul_f32_e32 v25, v25, v155
	v_mul_f32_e32 v26, v26, v156
	v_mul_f32_e32 v27, v27, v157
	v_mul_f32_e32 v28, v28, v158
	v_mul_f32_e32 v29, v29, v159
	v_mul_f32_e32 v30, v30, v160
	v_mul_f32_e32 v31, v31, v161
	v_cvt_pk_bf16_f32 v126, v24, v25
	v_cvt_pk_bf16_f32 v127, v26, v27
	v_cvt_pk_bf16_f32 v128, v28, v29
	v_cvt_pk_bf16_f32 v129, v30, v31
	v_lshlrev_b32_e32 v24, 16, v118
	v_and_b32_e32 v25, 0xffff0000, v118
	v_lshlrev_b32_e32 v26, 16, v119
	v_and_b32_e32 v27, 0xffff0000, v119
	v_lshlrev_b32_e32 v28, 16, v120
	v_and_b32_e32 v29, 0xffff0000, v120
	v_lshlrev_b32_e32 v30, 16, v121
	v_and_b32_e32 v31, 0xffff0000, v121
	v_mul_f32_e32 v24, v24, v169
	v_mul_f32_e32 v25, v25, v169
	v_mul_f32_e32 v26, v26, v169
	v_mul_f32_e32 v27, v27, v169
	v_mul_f32_e32 v28, v28, v169
	v_mul_f32_e32 v29, v29, v169
	v_mul_f32_e32 v30, v30, v169
	v_mul_f32_e32 v31, v31, v169
	v_mul_f32_e32 v24, v24, v224
	v_mul_f32_e32 v25, v25, v225
	v_mul_f32_e32 v26, v26, v226
	v_mul_f32_e32 v27, v27, v227
	v_mul_f32_e32 v28, v28, v228
	v_mul_f32_e32 v29, v29, v229
	v_mul_f32_e32 v30, v30, v230
	v_mul_f32_e32 v31, v31, v231
	v_cvt_pk_bf16_f32 v118, v24, v25
	v_cvt_pk_bf16_f32 v119, v26, v27
	v_cvt_pk_bf16_f32 v120, v28, v29
	v_cvt_pk_bf16_f32 v121, v30, v31
	v_lshlrev_b32_e32 v24, 16, v106
	v_and_b32_e32 v25, 0xffff0000, v106
	v_lshlrev_b32_e32 v26, 16, v107
	v_and_b32_e32 v27, 0xffff0000, v107
	v_lshlrev_b32_e32 v28, 16, v108
	v_and_b32_e32 v29, 0xffff0000, v108
	v_lshlrev_b32_e32 v30, 16, v109
	v_and_b32_e32 v31, 0xffff0000, v109
	v_mul_f32_e32 v24, v24, v169
	v_mul_f32_e32 v25, v25, v169
	v_mul_f32_e32 v26, v26, v169
	v_mul_f32_e32 v27, v27, v169
	v_mul_f32_e32 v28, v28, v169
	v_mul_f32_e32 v29, v29, v169
	v_mul_f32_e32 v30, v30, v169
	v_mul_f32_e32 v31, v31, v169
	v_mul_f32_e32 v24, v24, v232
	v_mul_f32_e32 v25, v25, v233
	v_mul_f32_e32 v26, v26, v234
	v_mul_f32_e32 v27, v27, v235
	v_mul_f32_e32 v28, v28, v236
	v_mul_f32_e32 v29, v29, v237
	v_mul_f32_e32 v30, v30, v238
	v_mul_f32_e32 v31, v31, v239
	v_cvt_pk_bf16_f32 v106, v24, v25
	v_cvt_pk_bf16_f32 v107, v26, v27
	v_cvt_pk_bf16_f32 v108, v28, v29
	v_cvt_pk_bf16_f32 v109, v30, v31
	v_lshlrev_b32_e32 v24, 16, v102
	v_and_b32_e32 v25, 0xffff0000, v102
	v_lshlrev_b32_e32 v26, 16, v103
	v_and_b32_e32 v27, 0xffff0000, v103
	v_lshlrev_b32_e32 v28, 16, v104
	v_and_b32_e32 v29, 0xffff0000, v104
	v_lshlrev_b32_e32 v30, 16, v105
	v_and_b32_e32 v31, 0xffff0000, v105
	v_mul_f32_e32 v24, v24, v169
	v_mul_f32_e32 v25, v25, v169
	v_mul_f32_e32 v26, v26, v169
	v_mul_f32_e32 v27, v27, v169
	v_mul_f32_e32 v28, v28, v169
	v_mul_f32_e32 v29, v29, v169
	v_mul_f32_e32 v30, v30, v169
	v_mul_f32_e32 v31, v31, v169
	v_mul_f32_e32 v24, v24, v240
	v_mul_f32_e32 v25, v25, v241
	v_mul_f32_e32 v26, v26, v242
	v_mul_f32_e32 v27, v27, v243
	v_mul_f32_e32 v28, v28, v244
	v_mul_f32_e32 v29, v29, v245
	v_mul_f32_e32 v30, v30, v246
	v_mul_f32_e32 v31, v31, v247
	v_cvt_pk_bf16_f32 v102, v24, v25
	v_cvt_pk_bf16_f32 v103, v26, v27
	v_cvt_pk_bf16_f32 v104, v28, v29
	v_cvt_pk_bf16_f32 v105, v30, v31
	v_lshlrev_b32_e32 v24, 16, v98
	v_and_b32_e32 v25, 0xffff0000, v98
	v_lshlrev_b32_e32 v26, 16, v99
	v_and_b32_e32 v27, 0xffff0000, v99
	v_lshlrev_b32_e32 v28, 16, v100
	v_and_b32_e32 v29, 0xffff0000, v100
	v_lshlrev_b32_e32 v30, 16, v101
	v_and_b32_e32 v31, 0xffff0000, v101
	v_mul_f32_e32 v24, v24, v169
	v_mul_f32_e32 v25, v25, v169
	v_mul_f32_e32 v26, v26, v169
	v_mul_f32_e32 v27, v27, v169
	v_mul_f32_e32 v28, v28, v169
	v_mul_f32_e32 v29, v29, v169
	v_mul_f32_e32 v30, v30, v169
	v_mul_f32_e32 v31, v31, v169
	v_mul_f32_e32 v24, v24, v248
	v_mul_f32_e32 v25, v25, v249
	v_mul_f32_e32 v26, v26, v250
	v_mul_f32_e32 v27, v27, v251
	v_mul_f32_e32 v28, v28, v164
	v_mul_f32_e32 v29, v29, v165
	v_mul_f32_e32 v30, v30, v166
	v_mul_f32_e32 v31, v31, v167
	v_cvt_pk_bf16_f32 v98, v24, v25
	v_cvt_pk_bf16_f32 v99, v26, v27
	v_cvt_pk_bf16_f32 v100, v28, v29
	v_cvt_pk_bf16_f32 v101, v30, v31
	v_bitop3_b32 v0, v96, v54, v55 bitop3:0xde
	v_add_u32_e32 v174, 0, v0
	s_waitcnt lgkmcnt(0)
	s_barrier
	ds_read_b128 v[0:3], v174 offset:32768
	ds_read_b128 v[16:19], v174 offset:40960
	s_waitcnt vmcnt(7) lgkmcnt(1)
	v_mfma_f32_32x32x16_bf16 v[0:15], v[0:3], v[114:117], 0
	ds_read_b128 v[34:37], v176 offset:32768
	ds_read_b128 v[38:41], v176 offset:40960
	v_and_b32_e32 v60, 63, v58
	s_add_i32 s3, 0, 0x10000
	v_lshlrev_b32_e32 v61, 3, v60
	s_mov_b64 s[4:5], 0xa000
	s_cmp_lg_u32 0, -1
	v_cmp_gt_u32_e64 s[42:43], 32, v60
	s_waitcnt lgkmcnt(2)
	v_mfma_f32_32x32x16_bf16 v[16:31], v[16:19], v[114:117], 0
	s_waitcnt vmcnt(6) lgkmcnt(1)
	v_mfma_f32_32x32x16_bf16 v[0:15], v[34:37], v[110:113], v[0:15]
	v_or_b32_e32 v34, 64, v96
	v_bitop3_b32 v34, v34, v54, v55 bitop3:0xde
	v_add_u32_e32 v175, 0, v34
	s_waitcnt lgkmcnt(0)
	v_mfma_f32_32x32x16_bf16 v[16:31], v[38:41], v[110:113], v[16:31]
	ds_read_b128 v[34:37], v175 offset:32768
	ds_read_b128 v[38:41], v175 offset:40960
	s_waitcnt vmcnt(5) lgkmcnt(1)
	v_mfma_f32_32x32x16_bf16 v[0:15], v[34:37], v[122:125], v[0:15]
	v_or_b32_e32 v34, 0x60, v96
	v_bitop3_b32 v34, v34, v54, v55 bitop3:0xde
	v_add_u32_e32 v173, 0, v34
	s_waitcnt lgkmcnt(0)
	v_mfma_f32_32x32x16_bf16 v[16:31], v[38:41], v[122:125], v[16:31]
	ds_read_b128 v[34:37], v173 offset:32768
	ds_read_b128 v[38:41], v173 offset:40960
	s_waitcnt vmcnt(4) lgkmcnt(1)
	v_mfma_f32_32x32x16_bf16 v[0:15], v[34:37], v[126:129], v[0:15]
	v_or_b32_e32 v34, 0x80, v96
	v_bitop3_b32 v34, v34, v54, v55 bitop3:0xde
	v_add_u32_e32 v172, 0, v34
	s_waitcnt lgkmcnt(0)
	v_mfma_f32_32x32x16_bf16 v[16:31], v[38:41], v[126:129], v[16:31]
	ds_read_b128 v[34:37], v172 offset:32768
	ds_read_b128 v[38:41], v172 offset:40960
	s_waitcnt vmcnt(3) lgkmcnt(1)
	v_mfma_f32_32x32x16_bf16 v[0:15], v[34:37], v[118:121], v[0:15]
	v_or_b32_e32 v34, 0xa0, v96
	v_bitop3_b32 v34, v34, v54, v55 bitop3:0xde
	v_add_u32_e32 v170, 0, v34
	s_waitcnt lgkmcnt(0)
	v_mfma_f32_32x32x16_bf16 v[16:31], v[38:41], v[118:121], v[16:31]
	ds_read_b128 v[34:37], v170 offset:32768
	ds_read_b128 v[38:41], v170 offset:40960
	s_waitcnt vmcnt(2) lgkmcnt(1)
	v_mfma_f32_32x32x16_bf16 v[0:15], v[34:37], v[106:109], v[0:15]
	v_or_b32_e32 v34, 0xc0, v96
	v_bitop3_b32 v34, v34, v54, v55 bitop3:0xde
	v_add_u32_e32 v171, 0, v34
	ds_read_b128 v[34:37], v171 offset:32768
	v_bitop3_b32 v54, v56, v54, v55 bitop3:0xde
	v_add_u32_e32 v177, 0, v54
	s_waitcnt lgkmcnt(1)
	v_mfma_f32_32x32x16_bf16 v[16:31], v[38:41], v[106:109], v[16:31]
	ds_read_b128 v[38:41], v171 offset:40960
	global_load_dwordx4 v[42:45], v[42:43], off
	s_nop 0
	global_load_dwordx4 v[46:49], v[46:47], off
	s_waitcnt vmcnt(3) lgkmcnt(1)
	v_mfma_f32_32x32x16_bf16 v[0:15], v[34:37], v[102:105], v[0:15]
	global_load_dwordx4 v[34:37], v[50:51], off
	s_nop 0
	global_load_dwordx4 v[50:53], v[52:53], off
	ds_read_b128 v[54:57], v177 offset:32768
	s_waitcnt lgkmcnt(1)
	v_mfma_f32_32x32x16_bf16 v[16:31], v[38:41], v[102:105], v[16:31]
	v_and_b32_e32 v38, 0x3fffffc0, v58
	v_lshl_add_u32 v164, v38, 2, s3
	v_and_b32_e32 v38, 0xc0, v59
	v_and_or_b32 v59, v61, 24, v38
	ds_read_b128 v[38:41], v177 offset:40960
	s_cselect_b32 s3, 0, 0
	v_lshl_add_u32 v165, v163, 2, v164
	s_waitcnt vmcnt(4) lgkmcnt(1)
	v_mfma_f32_32x32x16_bf16 v[0:15], v[54:57], v[98:101], v[0:15]
	v_lshlrev_b32_e32 v54, 1, v58
	v_and_b32_e32 v54, 32, v54
	v_and_b32_e32 v55, 0x100, v61
	v_or3_b32 v187, v59, v54, v55
	v_lshl_add_u64 v[54:55], v[32:33], 0, s[12:13]
	v_lshl_add_u64 v[56:57], s[44:45], 0, v[54:55]
	v_add_u32_e32 v169, s3, v187
	s_waitcnt lgkmcnt(0)
	v_mfma_f32_32x32x16_bf16 v[16:31], v[38:41], v[98:101], v[16:31]
	s_nop 2
	v_max_f32_e32 v38, v1, v1
	v_max_f32_e32 v39, v0, v0
	v_max_f32_e32 v38, v39, v38
	v_max3_f32 v38, v38, v2, v3
	v_max3_f32 v38, v38, v4, v5
	v_max3_f32 v38, v38, v6, v7
	v_max3_f32 v38, v38, v8, v9
	v_max3_f32 v38, v38, v10, v11
	v_max3_f32 v38, v38, v12, v13
	v_max3_f32 v58, v38, v14, v15
	v_lshl_add_u64 v[38:39], v[32:33], 0, s[4:5]
	v_lshl_add_u64 v[40:41], s[44:45], 0, v[38:39]
	v_lshl_add_u64 v[38:39], s[48:49], 0, v[38:39]
	global_load_dwordx4 v[146:149], v[40:41], off
	global_load_dwordx4 v[150:153], v[56:57], off
	v_lshl_add_u64 v[40:41], s[48:49], 0, v[54:55]
	global_load_dwordx4 v[154:157], v[38:39], off
	global_load_dwordx4 v[158:161], v[40:41], off
	v_max3_f32 v38, v58, v16, v17
	v_max3_f32 v38, v38, v18, v19
	v_max3_f32 v38, v38, v20, v21
	v_max3_f32 v38, v38, v22, v23
	v_max3_f32 v38, v38, v24, v25
	v_max3_f32 v38, v38, v26, v27
	v_max3_f32 v38, v38, v28, v29
	v_max3_f32 v38, v38, v30, v31
	v_mov_b32_e32 v39, v38
	s_nop 1
	v_permlane32_swap_b32_e32 v38, v39
	v_max_f32_e32 v39, v39, v39
	v_max_f32_e32 v38, v38, v38
	v_max_f32_e32 v38, v38, v39
	v_add_f32_e32 v39, 0x7149f2ca, v38
	v_cmp_ge_f32_e32 vcc, s35, v39
	s_cmp_eq_u64 vcc, exec
	v_max_f32_e32 v189, 0xf149f2ca, v38
	s_cselect_b64 s[40:41], -1, 0
	v_cndmask_b32_e64 v188, v189, v206, s[40:41]
	s_waitcnt vmcnt(4)
	s_waitcnt vmcnt(7)
	ds_write_b128 v184, v[42:45] offset:16384
	s_waitcnt vmcnt(6)
	ds_write_b128 v185, v[46:49] offset:16384
	s_waitcnt vmcnt(5)
	ds_write_b128 v182, v[34:37] offset:49152
	s_waitcnt vmcnt(4)
	ds_write_b128 v183, v[50:53] offset:49152
	v_mul_f32_e32 v34, 0xbe0293ee, v188
	v_fmamk_f32 v0, v0, 0x3e0293ee, v34
	v_exp_f32_e32 v35, v0
	v_fmamk_f32 v0, v1, 0x3e0293ee, v34
	v_exp_f32_e32 v36, v0
	v_fmamk_f32 v0, v2, 0x3e0293ee, v34
	v_exp_f32_e32 v37, v0
	v_fmamk_f32 v0, v3, 0x3e0293ee, v34
	v_exp_f32_e32 v38, v0
	v_fmamk_f32 v0, v4, 0x3e0293ee, v34
	v_exp_f32_e32 v39, v0
	v_fmamk_f32 v0, v5, 0x3e0293ee, v34
	v_exp_f32_e32 v40, v0
	v_fmamk_f32 v0, v6, 0x3e0293ee, v34
	v_exp_f32_e32 v41, v0
	v_fmamk_f32 v0, v7, 0x3e0293ee, v34
	v_exp_f32_e32 v42, v0
	v_fmamk_f32 v0, v8, 0x3e0293ee, v34
	v_exp_f32_e32 v8, v0
	v_fmamk_f32 v0, v9, 0x3e0293ee, v34
	v_exp_f32_e32 v9, v0
	v_fmamk_f32 v0, v10, 0x3e0293ee, v34
	v_exp_f32_e32 v10, v0
	v_fmamk_f32 v0, v11, 0x3e0293ee, v34
	v_exp_f32_e32 v11, v0
	v_fmamk_f32 v0, v12, 0x3e0293ee, v34
	v_exp_f32_e32 v12, v0
	v_fmamk_f32 v0, v13, 0x3e0293ee, v34
	v_fmamk_f32 v16, v16, 0x3e0293ee, v34
	v_fmamk_f32 v17, v17, 0x3e0293ee, v34
	v_fmamk_f32 v18, v18, 0x3e0293ee, v34
	v_fmamk_f32 v19, v19, 0x3e0293ee, v34
	v_fmamk_f32 v20, v20, 0x3e0293ee, v34
	v_fmamk_f32 v21, v21, 0x3e0293ee, v34
	v_fmamk_f32 v22, v22, 0x3e0293ee, v34
	v_fmamk_f32 v23, v23, 0x3e0293ee, v34
	v_fmamk_f32 v24, v24, 0x3e0293ee, v34
	v_fmamk_f32 v25, v25, 0x3e0293ee, v34
	v_fmamk_f32 v26, v26, 0x3e0293ee, v34
	v_fmamk_f32 v27, v27, 0x3e0293ee, v34
	v_fmamk_f32 v28, v28, 0x3e0293ee, v34
	v_fmamk_f32 v29, v29, 0x3e0293ee, v34
	v_fmamk_f32 v30, v30, 0x3e0293ee, v34
	v_fmamk_f32 v31, v31, 0x3e0293ee, v34
	v_exp_f32_e32 v13, v0
	v_fmamk_f32 v0, v14, 0x3e0293ee, v34
	v_fmac_f32_e32 v34, 0x3e0293ee, v15
	v_exp_f32_e32 v14, v0
	v_exp_f32_e32 v15, v34
	s_waitcnt lgkmcnt(0)
	s_barrier
	ds_read_b128 v[0:3], v174 offset:49152
	ds_read_b128 v[4:7], v174 offset:57344
	s_waitcnt lgkmcnt(1)
	v_mfma_f32_32x32x16_bf16 v[80:95], v[0:3], v[114:117], 0
	s_waitcnt lgkmcnt(0)
	v_mfma_f32_32x32x16_bf16 v[64:79], v[4:7], v[114:117], 0
	ds_read_b128 v[0:3], v176 offset:49152
	ds_read_b128 v[4:7], v176 offset:57344
	s_waitcnt lgkmcnt(1)
	v_mfma_f32_32x32x16_bf16 v[80:95], v[0:3], v[110:113], v[80:95]
	s_waitcnt lgkmcnt(0)
	v_mfma_f32_32x32x16_bf16 v[64:79], v[4:7], v[110:113], v[64:79]
	ds_read_b128 v[0:3], v175 offset:49152
	ds_read_b128 v[4:7], v175 offset:57344
	s_waitcnt lgkmcnt(1)
	v_mfma_f32_32x32x16_bf16 v[80:95], v[0:3], v[122:125], v[80:95]
	s_waitcnt lgkmcnt(0)
	v_mfma_f32_32x32x16_bf16 v[64:79], v[4:7], v[122:125], v[64:79]
	ds_read_b128 v[0:3], v173 offset:49152
	ds_read_b128 v[4:7], v173 offset:57344
	s_waitcnt lgkmcnt(1)
	v_mfma_f32_32x32x16_bf16 v[80:95], v[0:3], v[126:129], v[80:95]
	s_waitcnt lgkmcnt(0)
	v_mfma_f32_32x32x16_bf16 v[64:79], v[4:7], v[126:129], v[64:79]
	ds_read_b128 v[0:3], v172 offset:49152
	ds_read_b128 v[4:7], v172 offset:57344
	s_waitcnt lgkmcnt(1)
	v_mfma_f32_32x32x16_bf16 v[80:95], v[0:3], v[118:121], v[80:95]
	s_waitcnt lgkmcnt(0)
	v_mfma_f32_32x32x16_bf16 v[64:79], v[4:7], v[118:121], v[64:79]
	ds_read_b128 v[0:3], v170 offset:49152
	ds_read_b128 v[4:7], v170 offset:57344
	s_waitcnt lgkmcnt(1)
	v_mfma_f32_32x32x16_bf16 v[80:95], v[0:3], v[106:109], v[80:95]
	s_waitcnt lgkmcnt(0)
	v_mfma_f32_32x32x16_bf16 v[64:79], v[4:7], v[106:109], v[64:79]
	ds_read_b128 v[0:3], v171 offset:49152
	ds_read_b128 v[4:7], v171 offset:57344
	s_waitcnt lgkmcnt(1)
	v_mfma_f32_32x32x16_bf16 v[80:95], v[0:3], v[102:105], v[80:95]
	s_waitcnt lgkmcnt(0)
	v_mfma_f32_32x32x16_bf16 v[64:79], v[4:7], v[102:105], v[64:79]
	ds_read_b128 v[0:3], v177 offset:49152
	ds_read_b128 v[4:7], v177 offset:57344
	v_cvt_pk_bf16_f32 v48, v35, v36
	v_cvt_pk_bf16_f32 v49, v37, v38
	v_cvt_pk_bf16_f32 v50, v39, v40
	v_cvt_pk_bf16_f32 v51, v41, v42
	v_cvt_pk_bf16_f32 v190, v8, v9
	v_cvt_pk_bf16_f32 v191, v10, v11
	s_waitcnt lgkmcnt(1)
	v_mfma_f32_32x32x16_bf16 v[80:95], v[0:3], v[98:101], v[80:95]
	v_exp_f32_e32 v0, v16
	v_exp_f32_e32 v16, v24
	v_add_f32_e32 v24, 0, v35
	v_add_f32_e32 v24, v36, v24
	v_add_f32_e32 v24, v37, v24
	v_add_f32_e32 v24, v38, v24
	v_add_f32_e32 v24, v39, v24
	v_add_f32_e32 v24, v40, v24
	v_add_f32_e32 v24, v41, v24
	v_add_f32_e32 v24, v42, v24
	v_add_f32_e32 v24, v8, v24
	v_add_f32_e32 v24, v9, v24
	v_add_f32_e32 v24, v10, v24
	v_add_f32_e32 v24, v11, v24
	v_add_f32_e32 v24, v12, v24
	v_exp_f32_e32 v1, v17
	v_add_f32_e32 v24, v13, v24
	v_exp_f32_e32 v2, v18
	v_add_f32_e32 v24, v14, v24
	v_exp_f32_e32 v3, v19
	v_add_f32_e32 v24, v15, v24
	s_waitcnt lgkmcnt(0)
	v_mfma_f32_32x32x16_bf16 v[64:79], v[4:7], v[98:101], v[64:79]
	v_exp_f32_e32 v4, v20
	v_add_f32_e32 v24, v0, v24
	v_exp_f32_e32 v5, v21
	v_add_f32_e32 v24, v1, v24
	v_exp_f32_e32 v6, v22
	v_add_f32_e32 v24, v2, v24
	v_exp_f32_e32 v7, v23
	v_add_f32_e32 v24, v3, v24
	v_add_f32_e32 v24, v4, v24
	v_exp_f32_e32 v17, v25
	v_add_f32_e32 v24, v5, v24
	v_exp_f32_e32 v18, v26
	v_add_f32_e32 v24, v6, v24
	v_exp_f32_e32 v19, v27
	v_add_f32_e32 v24, v7, v24
	v_exp_f32_e32 v20, v28
	v_add_f32_e32 v24, v16, v24
	v_exp_f32_e32 v21, v29
	v_add_f32_e32 v24, v17, v24
	v_exp_f32_e32 v22, v30
	v_add_f32_e32 v24, v18, v24
	v_exp_f32_e32 v23, v31
	v_add_f32_e32 v24, v19, v24
	v_add_f32_e32 v24, v20, v24
	v_add_f32_e32 v24, v21, v24
	v_add_f32_e32 v24, v22, v24
	v_add_f32_e32 v166, v23, v24
	v_mov_b32_e32 v167, v166
	v_cvt_pk_bf16_f32 v192, v12, v13
	s_nop 1
	v_permlane32_swap_b32_e32 v166, v167
	v_permlane32_swap_b32_e32 v48, v50
	v_permlane32_swap_b32_e32 v49, v51
	v_cvt_pk_bf16_f32 v193, v14, v15
	v_permlane32_swap_b32_e32 v190, v192
	v_cvt_pk_bf16_f32 v194, v0, v1
	v_cvt_pk_bf16_f32 v195, v2, v3
	v_cvt_pk_bf16_f32 v196, v4, v5
	v_cvt_pk_bf16_f32 v197, v6, v7
	v_cvt_pk_bf16_f32 v198, v16, v17
	v_cvt_pk_bf16_f32 v199, v18, v19
	v_cvt_pk_bf16_f32 v200, v20, v21
	v_cvt_pk_bf16_f32 v201, v22, v23
	v_permlane32_swap_b32_e32 v191, v193
	v_permlane32_swap_b32_e32 v194, v196
	v_permlane32_swap_b32_e32 v195, v197
	v_permlane32_swap_b32_e32 v198, v200
	v_permlane32_swap_b32_e32 v199, v201
	s_mov_b64 s[4:5], 0xc000
	v_lshl_add_u64 v[0:1], v[32:33], 0, s[4:5]
	s_mov_b64 s[4:5], 0xe000
	v_lshl_add_u64 v[2:3], s[48:49], 0, v[0:1]
	v_lshl_add_u64 v[4:5], v[32:33], 0, s[4:5]
	v_lshl_add_u64 v[0:1], s[44:45], 0, v[0:1]
	v_lshl_add_u64 v[6:7], s[48:49], 0, v[4:5]
	global_load_dwordx4 v[130:133], v[2:3], off
	global_load_dwordx4 v[134:137], v[6:7], off
	v_lshl_add_u64 v[2:3], s[44:45], 0, v[4:5]
	global_load_dwordx4 v[138:141], v[0:1], off
	global_load_dwordx4 v[142:145], v[2:3], off
	ds_read_b64_tr_b16 v[0:1], v169 offset:0
	ds_read_b64_tr_b16 v[2:3], v169 offset:0x800
	ds_read_b64_tr_b16 v[16:17], v169 offset:0x1000
	ds_read_b64_tr_b16 v[18:19], v169 offset:0x1800
	ds_read_b64_tr_b16 v[20:21], v169 offset:0x2000
	ds_read_b64_tr_b16 v[22:23], v169 offset:0x2800
	ds_read_b64_tr_b16 v[24:25], v169 offset:0x3000
	ds_read_b64_tr_b16 v[26:27], v169 offset:0x3800
	s_waitcnt lgkmcnt(0)
	s_nop 0
	v_mfma_f32_32x32x16_bf16 v[0:15], v[48:51], v[0:3], 0
	v_mfma_f32_32x32x16_bf16 v[0:15], v[190:193], v[16:19], v[0:15]
	ds_read_b64_tr_b16 v[16:17], v169 offset:0x200
	ds_read_b64_tr_b16 v[18:19], v169 offset:0xa00
	ds_read_b64_tr_b16 v[32:33], v169 offset:0x1200
	ds_read_b64_tr_b16 v[34:35], v169 offset:0x1a00
	ds_read_b64_tr_b16 v[36:37], v169 offset:0x2200
	ds_read_b64_tr_b16 v[38:39], v169 offset:0x2a00
	ds_read_b64_tr_b16 v[40:41], v169 offset:0x3200
	v_mfma_f32_32x32x16_bf16 v[0:15], v[194:197], v[20:23], v[0:15]
	ds_read_b64_tr_b16 v[42:43], v169 offset:0x3a00
	s_waitcnt lgkmcnt(0)
	v_mfma_f32_32x32x16_bf16 v[0:15], v[198:201], v[24:27], v[0:15]
	v_mfma_f32_32x32x16_bf16 v[16:31], v[48:51], v[16:19], 0
	v_mfma_f32_32x32x16_bf16 v[16:31], v[190:193], v[32:35], v[16:31]
	ds_read_b64_tr_b16 v[32:33], v169 offset:0x400
	ds_read_b64_tr_b16 v[34:35], v169 offset:0xc00
	ds_read_b64_tr_b16 v[52:53], v169 offset:0x1400
	ds_read_b64_tr_b16 v[54:55], v169 offset:0x1c00
	ds_read_b64_tr_b16 v[56:57], v169 offset:0x2400
	ds_read_b64_tr_b16 v[58:59], v169 offset:0x2c00
	ds_read_b64_tr_b16 v[60:61], v169 offset:0x3400
	v_mfma_f32_32x32x16_bf16 v[16:31], v[194:197], v[36:39], v[16:31]
	ds_read_b64_tr_b16 v[62:63], v169 offset:0x3c00
	s_waitcnt lgkmcnt(0)
	v_mfma_f32_32x32x16_bf16 v[16:31], v[198:201], v[40:43], v[16:31]
	v_mfma_f32_32x32x16_bf16 v[32:47], v[48:51], v[32:35], 0
	v_mfma_f32_32x32x16_bf16 v[32:47], v[190:193], v[52:55], v[32:47]
	ds_read_b64_tr_b16 v[52:53], v169 offset:0x600
	ds_read_b64_tr_b16 v[54:55], v169 offset:0xe00
	ds_read_b64_tr_b16 v[224:225], v169 offset:0x1600
	ds_read_b64_tr_b16 v[226:227], v169 offset:0x1e00
	ds_read_b64_tr_b16 v[228:229], v169 offset:0x2600
	ds_read_b64_tr_b16 v[230:231], v169 offset:0x2e00
	ds_read_b64_tr_b16 v[232:233], v169 offset:0x3600
	v_mfma_f32_32x32x16_bf16 v[32:47], v[194:197], v[56:59], v[32:47]
	ds_read_b64_tr_b16 v[234:235], v169 offset:0x3e00
	s_waitcnt lgkmcnt(0)
	v_mfma_f32_32x32x16_bf16 v[32:47], v[198:201], v[60:63], v[32:47]
	v_mfma_f32_32x32x16_bf16 v[48:63], v[48:51], v[52:55], 0
	v_max_f32_e32 v168, v81, v81
	s_barrier
	s_waitcnt vmcnt(4)
	s_waitcnt vmcnt(4)
	ds_write_b128 v184, v[158:161]
	ds_write_b128 v185, v[154:157]
	ds_write_b128 v182, v[150:153] offset:32768
	ds_write_b128 v183, v[146:149] offset:32768
	v_mfma_f32_32x32x16_bf16 v[48:63], v[190:193], v[224:227], v[48:63]
	v_max_f32_e32 v190, v80, v80
	v_max_f32_e32 v168, v190, v168
	v_max3_f32 v168, v168, v82, v83
	v_max3_f32 v168, v168, v84, v85
	v_max3_f32 v168, v168, v86, v87
	v_max3_f32 v168, v168, v88, v89
	v_max3_f32 v168, v168, v90, v91
	v_max3_f32 v168, v168, v92, v93
	v_max3_f32 v168, v168, v94, v95
	v_max3_f32 v168, v168, v64, v65
	v_max3_f32 v168, v168, v66, v67
	v_max3_f32 v168, v168, v68, v69
	v_max3_f32 v168, v168, v70, v71
	v_max3_f32 v168, v168, v72, v73
	v_max3_f32 v168, v168, v74, v75
	v_mfma_f32_32x32x16_bf16 v[48:63], v[194:197], v[228:231], v[48:63]
	v_max3_f32 v168, v168, v76, v77
	v_max3_f32 v168, v168, v78, v79
	v_mov_b32_e32 v190, v168
	s_nop 1
	v_permlane32_swap_b32_e32 v168, v190
	v_max_f32_e32 v190, v190, v190
	v_max_f32_e32 v168, v168, v168
	v_max_f32_e32 v168, v168, v190
	v_sub_f32_e32 v190, v168, v188
	v_cmp_ge_f32_e32 vcc, s35, v190
	v_max_f32_e32 v190, v188, v168
	v_mfma_f32_32x32x16_bf16 v[48:63], v[198:201], v[232:235], v[48:63]
	v_sub_f32_e32 v168, v188, v190
	v_mul_f32_e32 v168, 0x3e0293ee, v168
	v_exp_f32_e32 v168, v168
	s_cmp_eq_u64 vcc, exec
	s_cselect_b64 s[44:45], -1, 0
	v_cndmask_b32_e64 v168, v168, 1.0, s[44:45]
	v_cmp_gt_f32_e32 vcc, 1.0, v168
	s_cbranch_vccz .LBB0_897
	s_and_saveexec_b64 s[48:49], s[42:43]
	ds_write_b32 v165, v168 offset:128
	s_or_b64 exec, exec, s[48:49]
	s_waitcnt lgkmcnt(0)
	v_add_u32_e32 v158, v164, v96
	ds_read_b128 v[146:149], v158 offset:224
	ds_read_b128 v[150:153], v158 offset:192
	ds_read_b128 v[154:157], v158 offset:160
	ds_read_b128 v[158:161], v158 offset:128
	v_mov_b32_e32 v222, 9
	s_waitcnt lgkmcnt(3)
	v_pk_mul_f32 v[12:13], v[12:13], v[146:147]
	s_waitcnt lgkmcnt(2)
	v_pk_mul_f32 v[8:9], v[8:9], v[150:151]
	s_waitcnt lgkmcnt(1)
	v_pk_mul_f32 v[4:5], v[4:5], v[154:155]
	v_pk_mul_f32 v[14:15], v[14:15], v[148:149]
	v_pk_mul_f32 v[10:11], v[10:11], v[152:153]
	v_pk_mul_f32 v[6:7], v[6:7], v[156:157]
	s_waitcnt lgkmcnt(0)
	v_pk_mul_f32 v[2:3], v[2:3], v[160:161]
	v_pk_mul_f32 v[0:1], v[0:1], v[158:159]
	v_pk_mul_f32 v[28:29], v[28:29], v[146:147]
	v_pk_mul_f32 v[24:25], v[24:25], v[150:151]
	v_pk_mul_f32 v[20:21], v[20:21], v[154:155]
	v_pk_mul_f32 v[30:31], v[30:31], v[148:149]
	v_pk_mul_f32 v[26:27], v[26:27], v[152:153]
	v_pk_mul_f32 v[22:23], v[22:23], v[156:157]
	v_pk_mul_f32 v[18:19], v[18:19], v[160:161]
	v_pk_mul_f32 v[16:17], v[16:17], v[158:159]
	v_pk_mul_f32 v[44:45], v[44:45], v[146:147]
	v_pk_mul_f32 v[40:41], v[40:41], v[150:151]
	v_pk_mul_f32 v[36:37], v[36:37], v[154:155]
	v_pk_mul_f32 v[46:47], v[46:47], v[148:149]
	v_pk_mul_f32 v[42:43], v[42:43], v[152:153]
	v_pk_mul_f32 v[38:39], v[38:39], v[156:157]
	v_pk_mul_f32 v[34:35], v[34:35], v[160:161]
	v_pk_mul_f32 v[32:33], v[32:33], v[158:159]
	v_pk_mul_f32 v[60:61], v[60:61], v[146:147]
	v_pk_mul_f32 v[56:57], v[56:57], v[150:151]
	v_pk_mul_f32 v[52:53], v[52:53], v[154:155]
	v_pk_mul_f32 v[62:63], v[62:63], v[148:149]
	v_pk_mul_f32 v[58:59], v[58:59], v[152:153]
	v_pk_mul_f32 v[54:55], v[54:55], v[156:157]
	v_pk_mul_f32 v[50:51], v[50:51], v[160:161]
	v_pk_mul_f32 v[48:49], v[48:49], v[158:159]
	s_branch .LBB0_898

.LBB0_909:
	s_lshr_b32 s2, s67, 4
	s_ashr_i32 s42, s67, 7
	s_bfe_u32 s3, s2, 0x10002
	s_ashr_i32 s43, s42, 31
	s_lshl_b32 s2, s67, 8
	s_lshl_b64 s[4:5], s[42:43], 12
	s_and_b32 s2, s2, 0xf00
	s_bfe_u32 s10, s67, 0x30004
	s_or_b32 s2, s4, s2
	s_add_u32 s4, s2, 0x1000
	s_addc_u32 s5, s5, 0
	s_lshl_b32 s2, s42, 1
	s_or_b32 s11, s2, s3
	s_lshl_b64 s[44:45], s[4:5], 10
	s_mul_i32 s4, s4, 0xc00
	s_add_u32 s4, s4, 0x3000000
	s_add_u32 s4, s39, s4
	s_addc_u32 s5, s52, 0
	s_lshl_b32 s2, s10, 7
	s_lshl_b32 s10, s10, 8
	s_add_u32 s50, s4, s10
	s_addc_u32 s51, s5, 0
	s_mul_hi_u32 s4, s11, 0x110000
	s_mul_i32 s5, s43, 0x110000
	v_mov_b32_e32 v74, v204
	s_add_i32 s4, s4, s5
	s_mul_i32 s11, s11, 0x110000
	s_add_u32 s48, s61, s11
	s_waitcnt vmcnt(5)
	v_ashrrev_i32_e32 v16, 4, v74
	s_waitcnt vmcnt(4)
	v_lshlrev_b32_e32 v22, 3, v74
	v_add_u32_e32 v18, 32, v16
	s_addc_u32 s49, s62, s4
	s_waitcnt vmcnt(0)
	v_and_b32_e32 v0, 0x78, v22
	v_ashrrev_i32_e32 v17, 31, v16
	v_ashrrev_i32_e32 v19, 31, v18
	s_add_u32 s40, s63, s11
	v_lshlrev_b32_e32 v23, 1, v0
	s_waitcnt vmcnt(3)
	v_lshlrev_b64 v[48:49], 8, v[16:17]
	v_lshlrev_b64 v[12:13], 8, v[18:19]
	s_addc_u32 s41, s64, s4
	v_or_b32_e32 v50, v48, v23
	v_mov_b32_e32 v51, v49
	v_or_b32_e32 v12, v12, v23
	v_lshl_add_u64 v[0:1], s[40:41], 0, v[50:51]
	v_lshl_add_u64 v[4:5], s[40:41], 0, v[12:13]
	global_load_dwordx4 v[0:3], v[0:1], off
	s_nop 0
	global_load_dwordx4 v[4:7], v[4:5], off
	v_lshl_add_u64 v[8:9], s[48:49], 0, v[50:51]
	v_lshl_add_u64 v[12:13], s[48:49], 0, v[12:13]
	global_load_dwordx4 v[8:11], v[8:9], off
	v_ashrrev_i32_e32 v52, 1, v74
	global_load_dwordx4 v[12:15], v[12:13], off
	s_movk_i32 s4, 0xffe0
	v_bfi_b32 v20, s4, v52, v74
	v_ashrrev_i32_e32 v21, 31, v20
	v_bfe_u32 v186, v74, 5, 1
	v_mul_u32_u24_e32 v20, 0xc00, v20
	v_lshl_add_u64 v[20:21], s[50:51], 0, v[20:21]
	v_lshlrev_b32_e32 v96, 4, v186
	v_lshl_add_u64 v[20:21], v[20:21], 0, v[96:97]
	global_load_dwordx4 v[118:121], v[20:21], off
	global_load_dwordx4 v[114:117], v[20:21], off offset:32
	global_load_dwordx4 v[126:129], v[20:21], off offset:64
	global_load_dwordx4 v[122:125], v[20:21], off offset:96
	global_load_dwordx4 v[110:113], v[20:21], off offset:128
	global_load_dwordx4 v[106:109], v[20:21], off offset:160
	global_load_dwordx4 v[102:105], v[20:21], off offset:192
	global_load_dwordx4 v[98:101], v[20:21], off offset:224
	v_and_b32_e32 v19, 0xfffff0, v16
	v_lshlrev_b32_e32 v24, 1, v16
	v_lshrrev_b32_e32 v25, 1, v16
	v_and_b32_e32 v26, 3, v16
	v_and_or_b32 v19, v24, 8, v19
	v_and_or_b32 v24, v25, 4, v26
	v_and_b32_e32 v25, 0xfffff0, v18
	v_lshlrev_b32_e32 v26, 1, v18
	v_bfe_u32 v22, v22, 5, 2
	v_lshrrev_b32_e32 v19, 1, v19
	v_and_or_b32 v25, v26, 8, v25
	v_or_b32_e32 v19, v19, v22
	v_lshrrev_b32_e32 v25, 1, v25
	v_lshlrev_b32_e32 v24, 6, v24
	v_and_b32_e32 v27, 48, v23
	v_lshlrev_b32_e32 v19, 9, v19
	v_or_b32_e32 v22, v25, v22
	v_or3_b32 v19, v19, v24, v27
	v_lshlrev_b32_e32 v22, 9, v22
	v_or3_b32 v22, v22, v24, v27
	v_add_u32_e32 v192, 0, v19
	v_and_b32_e32 v17, 0xf0, v74
	v_lshlrev_b32_e32 v16, 8, v16
	v_add_u32_e32 v193, 0, v22
	s_waitcnt vmcnt(0)
	v_bitop3_b32 v16, v23, v16, v17 bitop3:0xde
	v_and_b32_e32 v187, 31, v74
	v_lshlrev_b32_e32 v53, 4, v74
	v_add_u32_e32 v194, 0, v16
	s_add_i32 s5, 0, 0x10000
	s_mov_b64 s[10:11], 0x4000
	v_and_b32_e32 v182, 0xffffffe0, v52
	v_and_b32_e32 v75, 63, v74
	s_cmp_lg_u32 0, -1
	s_mul_i32 s4, s3, 0x110000
	s_waitcnt vmcnt(11)
	ds_write_b128 v192, v[0:3]
	s_waitcnt vmcnt(10)
	ds_write_b128 v193, v[4:7]
	v_lshlrev_b32_e32 v0, 8, v18
	v_bitop3_b32 v0, v23, v0, v17 bitop3:0xde
	v_add_u32_e32 v195, 0, v0
	s_waitcnt vmcnt(9)
	ds_write_b128 v194, v[8:11] offset:32768
	s_waitcnt vmcnt(8)
	ds_write_b128 v195, v[12:15] offset:32768
	s_load_dwordx2 s[100:101], s[88:89], 0x80
	v_lshlrev_b32_e32 v175, 5, v186
	v_mov_b32_e32 v188, s44
	v_lshrrev_b32_e32 v188, 10, v188
	v_lshrrev_b32_e32 v189, 1, v74
	v_and_b32_e32 v189, 0xffe0, v189
	v_and_or_b32 v189, v74, 31, v189
	v_add_u32_e32 v188, v188, v189
	v_bfe_u32 v94, v188, 6, 6
	v_and_b32_e32 v95, 63, v188
	v_cvt_f32_ubyte0_e32 v94, v94
	v_cvt_f32_ubyte0_e32 v95, v95
	v_lshlrev_b32_e32 v190, 4, v186
	v_add_u32_e32 v191, 0, v190
	v_cvt_f32_ubyte0_e32 v78, v191
	v_add_u32_e32 v191, 2, v190
	v_cvt_f32_ubyte0_e32 v79, v191
	v_add_u32_e32 v191, 4, v190
	v_cvt_f32_ubyte0_e32 v80, v191
	v_add_u32_e32 v191, 6, v190
	v_cvt_f32_ubyte0_e32 v81, v191
	v_add_u32_e32 v191, 8, v190
	v_cvt_f32_ubyte0_e32 v82, v191
	v_add_u32_e32 v191, 10, v190
	v_cvt_f32_ubyte0_e32 v83, v191
	v_add_u32_e32 v191, 12, v190
	v_cvt_f32_ubyte0_e32 v84, v191
	v_add_u32_e32 v191, 14, v190
	v_cvt_f32_ubyte0_e32 v85, v191
	v_add_u32_e32 v191, 32, v190
	v_cvt_f32_ubyte0_e32 v86, v191
	v_add_u32_e32 v191, 34, v190
	v_cvt_f32_ubyte0_e32 v87, v191
	v_add_u32_e32 v191, 36, v190
	v_cvt_f32_ubyte0_e32 v88, v191
	v_add_u32_e32 v191, 38, v190
	v_cvt_f32_ubyte0_e32 v89, v191
	v_add_u32_e32 v191, 40, v190
	v_cvt_f32_ubyte0_e32 v90, v191
	v_add_u32_e32 v191, 42, v190
	v_cvt_f32_ubyte0_e32 v91, v191
	v_add_u32_e32 v191, 44, v190
	v_cvt_f32_ubyte0_e32 v92, v191
	v_add_u32_e32 v191, 46, v190
	v_cvt_f32_ubyte0_e32 v93, v191
	v_mul_f32_e32 v78, 0xbe549a78, v78
	v_mul_f32_e32 v79, 0xbe549a78, v79
	v_mul_f32_e32 v80, 0xbe549a78, v80
	v_mul_f32_e32 v81, 0xbe549a78, v81
	v_mul_f32_e32 v82, 0xbe549a78, v82
	v_mul_f32_e32 v83, 0xbe549a78, v83
	v_mul_f32_e32 v84, 0xbe549a78, v84
	v_mul_f32_e32 v85, 0xbe549a78, v85
	v_mul_f32_e32 v86, 0xbe549a78, v86
	v_mul_f32_e32 v87, 0xbe549a78, v87
	v_mul_f32_e32 v88, 0xbe549a78, v88
	v_mul_f32_e32 v89, 0xbe549a78, v89
	v_mul_f32_e32 v90, 0xbe549a78, v90
	v_mul_f32_e32 v91, 0xbe549a78, v91
	v_mul_f32_e32 v92, 0xbe549a78, v92
	v_mul_f32_e32 v93, 0xbe549a78, v93
	v_exp_f32_e32 v78, v78
	v_exp_f32_e32 v79, v79
	v_exp_f32_e32 v80, v80
	v_exp_f32_e32 v81, v81
	v_exp_f32_e32 v82, v82
	v_exp_f32_e32 v83, v83
	v_exp_f32_e32 v84, v84
	v_exp_f32_e32 v85, v85
	v_exp_f32_e32 v86, v86
	v_exp_f32_e32 v87, v87
	v_exp_f32_e32 v88, v88
	v_exp_f32_e32 v89, v89
	v_exp_f32_e32 v90, v90
	v_exp_f32_e32 v91, v91
	v_exp_f32_e32 v92, v92
	v_exp_f32_e32 v93, v93
	s_waitcnt lgkmcnt(0)
	global_load_dwordx4 v[130:133], v175, s[100:101] offset:0
	global_load_dwordx4 v[134:137], v175, s[100:101] offset:16
	global_load_dwordx4 v[138:141], v175, s[100:101] offset:64
	global_load_dwordx4 v[142:145], v175, s[100:101] offset:80
	global_load_dwordx4 v[146:149], v175, s[100:101] offset:128
	global_load_dwordx4 v[150:153], v175, s[100:101] offset:144
	global_load_dwordx4 v[154:157], v175, s[100:101] offset:192
	global_load_dwordx4 v[158:161], v175, s[100:101] offset:208
	global_load_dwordx4 v[224:227], v175, s[100:101] offset:256
	global_load_dwordx4 v[228:231], v175, s[100:101] offset:272
	global_load_dwordx4 v[232:235], v175, s[100:101] offset:320
	global_load_dwordx4 v[236:239], v175, s[100:101] offset:336
	global_load_dwordx4 v[240:243], v175, s[100:101] offset:384
	global_load_dwordx4 v[244:247], v175, s[100:101] offset:400
	global_load_dwordx4 v[248:251], v175, s[100:101] offset:448
	global_load_dwordx4 v[164:167], v175, s[100:101] offset:464
	v_lshlrev_b32_e32 v24, 16, v118
	v_and_b32_e32 v25, 0xffff0000, v118
	v_lshlrev_b32_e32 v26, 16, v119
	v_and_b32_e32 v27, 0xffff0000, v119
	v_lshlrev_b32_e32 v28, 16, v120
	v_and_b32_e32 v29, 0xffff0000, v120
	v_lshlrev_b32_e32 v30, 16, v121
	v_and_b32_e32 v31, 0xffff0000, v121
	v_mul_f32_e32 v168, v24, v24
	v_fmac_f32_e32 v168, v25, v25
	v_fmac_f32_e32 v168, v26, v26
	v_fmac_f32_e32 v168, v27, v27
	v_fmac_f32_e32 v168, v28, v28
	v_fmac_f32_e32 v168, v29, v29
	v_fmac_f32_e32 v168, v30, v30
	v_fmac_f32_e32 v168, v31, v31
	v_lshlrev_b32_e32 v24, 16, v114
	v_and_b32_e32 v25, 0xffff0000, v114
	v_lshlrev_b32_e32 v26, 16, v115
	v_and_b32_e32 v27, 0xffff0000, v115
	v_lshlrev_b32_e32 v28, 16, v116
	v_and_b32_e32 v29, 0xffff0000, v116
	v_lshlrev_b32_e32 v30, 16, v117
	v_and_b32_e32 v31, 0xffff0000, v117
	v_fmac_f32_e32 v168, v24, v24
	v_fmac_f32_e32 v168, v25, v25
	v_fmac_f32_e32 v168, v26, v26
	v_fmac_f32_e32 v168, v27, v27
	v_fmac_f32_e32 v168, v28, v28
	v_fmac_f32_e32 v168, v29, v29
	v_fmac_f32_e32 v168, v30, v30
	v_fmac_f32_e32 v168, v31, v31
	v_lshlrev_b32_e32 v24, 16, v126
	v_and_b32_e32 v25, 0xffff0000, v126
	v_lshlrev_b32_e32 v26, 16, v127
	v_and_b32_e32 v27, 0xffff0000, v127
	v_lshlrev_b32_e32 v28, 16, v128
	v_and_b32_e32 v29, 0xffff0000, v128
	v_lshlrev_b32_e32 v30, 16, v129
	v_and_b32_e32 v31, 0xffff0000, v129
	v_fmac_f32_e32 v168, v24, v24
	v_fmac_f32_e32 v168, v25, v25
	v_fmac_f32_e32 v168, v26, v26
	v_fmac_f32_e32 v168, v27, v27
	v_fmac_f32_e32 v168, v28, v28
	v_fmac_f32_e32 v168, v29, v29
	v_fmac_f32_e32 v168, v30, v30
	v_fmac_f32_e32 v168, v31, v31
	v_lshlrev_b32_e32 v24, 16, v122
	v_and_b32_e32 v25, 0xffff0000, v122
	v_lshlrev_b32_e32 v26, 16, v123
	v_and_b32_e32 v27, 0xffff0000, v123
	v_lshlrev_b32_e32 v28, 16, v124
	v_and_b32_e32 v29, 0xffff0000, v124
	v_lshlrev_b32_e32 v30, 16, v125
	v_and_b32_e32 v31, 0xffff0000, v125
	v_fmac_f32_e32 v168, v24, v24
	v_fmac_f32_e32 v168, v25, v25
	v_fmac_f32_e32 v168, v26, v26
	v_fmac_f32_e32 v168, v27, v27
	v_fmac_f32_e32 v168, v28, v28
	v_fmac_f32_e32 v168, v29, v29
	v_fmac_f32_e32 v168, v30, v30
	v_fmac_f32_e32 v168, v31, v31
	v_lshlrev_b32_e32 v24, 16, v110
	v_and_b32_e32 v25, 0xffff0000, v110
	v_lshlrev_b32_e32 v26, 16, v111
	v_and_b32_e32 v27, 0xffff0000, v111
	v_lshlrev_b32_e32 v28, 16, v112
	v_and_b32_e32 v29, 0xffff0000, v112
	v_lshlrev_b32_e32 v30, 16, v113
	v_and_b32_e32 v31, 0xffff0000, v113
	v_fmac_f32_e32 v168, v24, v24
	v_fmac_f32_e32 v168, v25, v25
	v_fmac_f32_e32 v168, v26, v26
	v_fmac_f32_e32 v168, v27, v27
	v_fmac_f32_e32 v168, v28, v28
	v_fmac_f32_e32 v168, v29, v29
	v_fmac_f32_e32 v168, v30, v30
	v_fmac_f32_e32 v168, v31, v31
	v_lshlrev_b32_e32 v24, 16, v106
	v_and_b32_e32 v25, 0xffff0000, v106
	v_lshlrev_b32_e32 v26, 16, v107
	v_and_b32_e32 v27, 0xffff0000, v107
	v_lshlrev_b32_e32 v28, 16, v108
	v_and_b32_e32 v29, 0xffff0000, v108
	v_lshlrev_b32_e32 v30, 16, v109
	v_and_b32_e32 v31, 0xffff0000, v109
	v_fmac_f32_e32 v168, v24, v24
	v_fmac_f32_e32 v168, v25, v25
	v_fmac_f32_e32 v168, v26, v26
	v_fmac_f32_e32 v168, v27, v27
	v_fmac_f32_e32 v168, v28, v28
	v_fmac_f32_e32 v168, v29, v29
	v_fmac_f32_e32 v168, v30, v30
	v_fmac_f32_e32 v168, v31, v31
	v_lshlrev_b32_e32 v24, 16, v102
	v_and_b32_e32 v25, 0xffff0000, v102
	v_lshlrev_b32_e32 v26, 16, v103
	v_and_b32_e32 v27, 0xffff0000, v103
	v_lshlrev_b32_e32 v28, 16, v104
	v_and_b32_e32 v29, 0xffff0000, v104
	v_lshlrev_b32_e32 v30, 16, v105
	v_and_b32_e32 v31, 0xffff0000, v105
	v_fmac_f32_e32 v168, v24, v24
	v_fmac_f32_e32 v168, v25, v25
	v_fmac_f32_e32 v168, v26, v26
	v_fmac_f32_e32 v168, v27, v27
	v_fmac_f32_e32 v168, v28, v28
	v_fmac_f32_e32 v168, v29, v29
	v_fmac_f32_e32 v168, v30, v30
	v_fmac_f32_e32 v168, v31, v31
	v_lshlrev_b32_e32 v24, 16, v98
	v_and_b32_e32 v25, 0xffff0000, v98
	v_lshlrev_b32_e32 v26, 16, v99
	v_and_b32_e32 v27, 0xffff0000, v99
	v_lshlrev_b32_e32 v28, 16, v100
	v_and_b32_e32 v29, 0xffff0000, v100
	v_lshlrev_b32_e32 v30, 16, v101
	v_and_b32_e32 v31, 0xffff0000, v101
	v_fmac_f32_e32 v168, v24, v24
	v_fmac_f32_e32 v168, v25, v25
	v_fmac_f32_e32 v168, v26, v26
	v_fmac_f32_e32 v168, v27, v27
	v_fmac_f32_e32 v168, v28, v28
	v_fmac_f32_e32 v168, v29, v29
	v_fmac_f32_e32 v168, v30, v30
	v_fmac_f32_e32 v168, v31, v31
	v_mov_b32_e32 v170, v168
	s_nop 1
	v_permlane32_swap_b32_e32 v168, v170
	v_add_f32_e32 v168, v168, v170
	v_fmamk_f32 v168, v168, 0x3c000000, v207
	v_rsq_f32_e32 v169, v168
	s_nop 0
	v_mul_f32_e32 v170, v168, v169
	v_fma_f32 v170, -v170, v169, 1.0
	v_mul_f32_e32 v170, 0.5, v170
	v_fmac_f32_e32 v169, v169, v170
	s_waitcnt vmcnt(0)
	v_lshlrev_b32_e32 v24, 16, v118
	v_and_b32_e32 v25, 0xffff0000, v118
	v_lshlrev_b32_e32 v26, 16, v119
	v_and_b32_e32 v27, 0xffff0000, v119
	v_lshlrev_b32_e32 v28, 16, v120
	v_and_b32_e32 v29, 0xffff0000, v120
	v_lshlrev_b32_e32 v30, 16, v121
	v_and_b32_e32 v31, 0xffff0000, v121
	v_lshlrev_b32_e32 v34, 16, v126
	v_and_b32_e32 v35, 0xffff0000, v126
	v_lshlrev_b32_e32 v36, 16, v127
	v_and_b32_e32 v37, 0xffff0000, v127
	v_lshlrev_b32_e32 v38, 16, v128
	v_and_b32_e32 v39, 0xffff0000, v128
	v_lshlrev_b32_e32 v40, 16, v129
	v_and_b32_e32 v41, 0xffff0000, v129
	v_mul_f32_e32 v24, v24, v169
	v_mul_f32_e32 v25, v25, v169
	v_mul_f32_e32 v26, v26, v169
	v_mul_f32_e32 v27, v27, v169
	v_mul_f32_e32 v28, v28, v169
	v_mul_f32_e32 v29, v29, v169
	v_mul_f32_e32 v30, v30, v169
	v_mul_f32_e32 v31, v31, v169
	v_mul_f32_e32 v24, v24, v130
	v_mul_f32_e32 v25, v25, v131
	v_mul_f32_e32 v26, v26, v132
	v_mul_f32_e32 v27, v27, v133
	v_mul_f32_e32 v28, v28, v134
	v_mul_f32_e32 v29, v29, v135
	v_mul_f32_e32 v30, v30, v136
	v_mul_f32_e32 v31, v31, v137
	v_mul_f32_e32 v34, v34, v169
	v_mul_f32_e32 v35, v35, v169
	v_mul_f32_e32 v36, v36, v169
	v_mul_f32_e32 v37, v37, v169
	v_mul_f32_e32 v38, v38, v169
	v_mul_f32_e32 v39, v39, v169
	v_mul_f32_e32 v40, v40, v169
	v_mul_f32_e32 v41, v41, v169
	v_mul_f32_e32 v34, v34, v146
	v_mul_f32_e32 v35, v35, v147
	v_mul_f32_e32 v36, v36, v148
	v_mul_f32_e32 v37, v37, v149
	v_mul_f32_e32 v38, v38, v150
	v_mul_f32_e32 v39, v39, v151
	v_mul_f32_e32 v40, v40, v152
	v_mul_f32_e32 v41, v41, v153
	v_mul_f32_e32 v60, v78, v94
	v_mul_f32_e32 v61, v79, v94
	v_mul_f32_e32 v62, v80, v94
	v_mul_f32_e32 v63, v81, v94
	v_mul_f32_e32 v64, v82, v94
	v_mul_f32_e32 v65, v83, v94
	v_mul_f32_e32 v66, v84, v94
	v_mul_f32_e32 v67, v85, v94
	v_mul_f32_e32 v68, 0.15915494, v60
	v_mul_f32_e32 v69, 0.15915494, v61
	v_mul_f32_e32 v70, 0.15915494, v62
	v_mul_f32_e32 v71, 0.15915494, v63
	v_mul_f32_e32 v72, 0.15915494, v64
	v_mul_f32_e32 v73, 0.15915494, v65
	v_mul_f32_e32 v76, 0.15915494, v66
	v_mul_f32_e32 v77, 0.15915494, v67
	v_rndne_f32_e32 v68, v68
	v_rndne_f32_e32 v69, v69
	v_rndne_f32_e32 v70, v70
	v_rndne_f32_e32 v71, v71
	v_rndne_f32_e32 v72, v72
	v_rndne_f32_e32 v73, v73
	v_rndne_f32_e32 v76, v76
	v_rndne_f32_e32 v77, v77
	v_fmac_f32_e32 v60, 0xc0c90fdb, v68
	v_fmac_f32_e32 v61, 0xc0c90fdb, v69
	v_fmac_f32_e32 v62, 0xc0c90fdb, v70
	v_fmac_f32_e32 v63, 0xc0c90fdb, v71
	v_fmac_f32_e32 v64, 0xc0c90fdb, v72
	v_fmac_f32_e32 v65, 0xc0c90fdb, v73
	v_fmac_f32_e32 v66, 0xc0c90fdb, v76
	v_fmac_f32_e32 v67, 0xc0c90fdb, v77
	v_fmac_f32_e32 v60, 0x343bbd2e, v68
	v_fmac_f32_e32 v61, 0x343bbd2e, v69
	v_fmac_f32_e32 v62, 0x343bbd2e, v70
	v_fmac_f32_e32 v63, 0x343bbd2e, v71
	v_fmac_f32_e32 v64, 0x343bbd2e, v72
	v_fmac_f32_e32 v65, 0x343bbd2e, v73
	v_fmac_f32_e32 v66, 0x343bbd2e, v76
	v_fmac_f32_e32 v67, 0x343bbd2e, v77
	v_mul_f32_e32 v60, 0.15915494, v60
	v_mul_f32_e32 v61, 0.15915494, v61
	v_mul_f32_e32 v62, 0.15915494, v62
	v_mul_f32_e32 v63, 0.15915494, v63
	v_mul_f32_e32 v64, 0.15915494, v64
	v_mul_f32_e32 v65, 0.15915494, v65
	v_mul_f32_e32 v66, 0.15915494, v66
	v_mul_f32_e32 v67, 0.15915494, v67
	v_sin_f32_e32 v68, v60
	v_sin_f32_e32 v69, v61
	v_sin_f32_e32 v70, v62
	v_sin_f32_e32 v71, v63
	v_sin_f32_e32 v72, v64
	v_sin_f32_e32 v73, v65
	v_sin_f32_e32 v76, v66
	v_sin_f32_e32 v77, v67
	v_cos_f32_e32 v60, v60
	v_cos_f32_e32 v61, v61
	v_cos_f32_e32 v62, v62
	v_cos_f32_e32 v63, v63
	v_cos_f32_e32 v64, v64
	v_cos_f32_e32 v65, v65
	v_cos_f32_e32 v66, v66
	v_cos_f32_e32 v67, v67
	s_nop 0
	v_mul_f32_e32 v171, v68, v34
	v_mul_f32_e32 v172, v60, v34
	v_fmac_f32_e32 v172, v68, v24
	v_fma_f32 v24, v60, v24, -v171
	v_mov_b32_e32 v34, v172
	v_mul_f32_e32 v171, v69, v35
	v_mul_f32_e32 v172, v61, v35
	v_fmac_f32_e32 v172, v69, v25
	v_fma_f32 v25, v61, v25, -v171
	v_mov_b32_e32 v35, v172
	v_mul_f32_e32 v171, v70, v36
	v_mul_f32_e32 v172, v62, v36
	v_fmac_f32_e32 v172, v70, v26
	v_fma_f32 v26, v62, v26, -v171
	v_mov_b32_e32 v36, v172
	v_mul_f32_e32 v171, v71, v37
	v_mul_f32_e32 v172, v63, v37
	v_fmac_f32_e32 v172, v71, v27
	v_fma_f32 v27, v63, v27, -v171
	v_mov_b32_e32 v37, v172
	v_mul_f32_e32 v171, v72, v38
	v_mul_f32_e32 v172, v64, v38
	v_fmac_f32_e32 v172, v72, v28
	v_fma_f32 v28, v64, v28, -v171
	v_mov_b32_e32 v38, v172
	v_mul_f32_e32 v171, v73, v39
	v_mul_f32_e32 v172, v65, v39
	v_fmac_f32_e32 v172, v73, v29
	v_fma_f32 v29, v65, v29, -v171
	v_mov_b32_e32 v39, v172
	v_mul_f32_e32 v171, v76, v40
	v_mul_f32_e32 v172, v66, v40
	v_fmac_f32_e32 v172, v76, v30
	v_fma_f32 v30, v66, v30, -v171
	v_mov_b32_e32 v40, v172
	v_mul_f32_e32 v171, v77, v41
	v_mul_f32_e32 v172, v67, v41
	v_fmac_f32_e32 v172, v77, v31
	v_fma_f32 v31, v67, v31, -v171
	v_mov_b32_e32 v41, v172
	v_cvt_pk_bf16_f32 v118, v24, v25
	v_cvt_pk_bf16_f32 v119, v26, v27
	v_cvt_pk_bf16_f32 v120, v28, v29
	v_cvt_pk_bf16_f32 v121, v30, v31
	v_cvt_pk_bf16_f32 v126, v34, v35
	v_cvt_pk_bf16_f32 v127, v36, v37
	v_cvt_pk_bf16_f32 v128, v38, v39
	v_cvt_pk_bf16_f32 v129, v40, v41
	v_lshlrev_b32_e32 v24, 16, v114
	v_and_b32_e32 v25, 0xffff0000, v114
	v_lshlrev_b32_e32 v26, 16, v115
	v_and_b32_e32 v27, 0xffff0000, v115
	v_lshlrev_b32_e32 v28, 16, v116
	v_and_b32_e32 v29, 0xffff0000, v116
	v_lshlrev_b32_e32 v30, 16, v117
	v_and_b32_e32 v31, 0xffff0000, v117
	v_lshlrev_b32_e32 v34, 16, v122
	v_and_b32_e32 v35, 0xffff0000, v122
	v_lshlrev_b32_e32 v36, 16, v123
	v_and_b32_e32 v37, 0xffff0000, v123
	v_lshlrev_b32_e32 v38, 16, v124
	v_and_b32_e32 v39, 0xffff0000, v124
	v_lshlrev_b32_e32 v40, 16, v125
	v_and_b32_e32 v41, 0xffff0000, v125
	v_mul_f32_e32 v24, v24, v169
	v_mul_f32_e32 v25, v25, v169
	v_mul_f32_e32 v26, v26, v169
	v_mul_f32_e32 v27, v27, v169
	v_mul_f32_e32 v28, v28, v169
	v_mul_f32_e32 v29, v29, v169
	v_mul_f32_e32 v30, v30, v169
	v_mul_f32_e32 v31, v31, v169
	v_mul_f32_e32 v24, v24, v138
	v_mul_f32_e32 v25, v25, v139
	v_mul_f32_e32 v26, v26, v140
	v_mul_f32_e32 v27, v27, v141
	v_mul_f32_e32 v28, v28, v142
	v_mul_f32_e32 v29, v29, v143
	v_mul_f32_e32 v30, v30, v144
	v_mul_f32_e32 v31, v31, v145
	v_mul_f32_e32 v34, v34, v169
	v_mul_f32_e32 v35, v35, v169
	v_mul_f32_e32 v36, v36, v169
	v_mul_f32_e32 v37, v37, v169
	v_mul_f32_e32 v38, v38, v169
	v_mul_f32_e32 v39, v39, v169
	v_mul_f32_e32 v40, v40, v169
	v_mul_f32_e32 v41, v41, v169
	v_mul_f32_e32 v34, v34, v154
	v_mul_f32_e32 v35, v35, v155
	v_mul_f32_e32 v36, v36, v156
	v_mul_f32_e32 v37, v37, v157
	v_mul_f32_e32 v38, v38, v158
	v_mul_f32_e32 v39, v39, v159
	v_mul_f32_e32 v40, v40, v160
	v_mul_f32_e32 v41, v41, v161
	v_mul_f32_e32 v60, v86, v94
	v_mul_f32_e32 v61, v87, v94
	v_mul_f32_e32 v62, v88, v94
	v_mul_f32_e32 v63, v89, v94
	v_mul_f32_e32 v64, v90, v94
	v_mul_f32_e32 v65, v91, v94
	v_mul_f32_e32 v66, v92, v94
	v_mul_f32_e32 v67, v93, v94
	v_mul_f32_e32 v68, 0.15915494, v60
	v_mul_f32_e32 v69, 0.15915494, v61
	v_mul_f32_e32 v70, 0.15915494, v62
	v_mul_f32_e32 v71, 0.15915494, v63
	v_mul_f32_e32 v72, 0.15915494, v64
	v_mul_f32_e32 v73, 0.15915494, v65
	v_mul_f32_e32 v76, 0.15915494, v66
	v_mul_f32_e32 v77, 0.15915494, v67
	v_rndne_f32_e32 v68, v68
	v_rndne_f32_e32 v69, v69
	v_rndne_f32_e32 v70, v70
	v_rndne_f32_e32 v71, v71
	v_rndne_f32_e32 v72, v72
	v_rndne_f32_e32 v73, v73
	v_rndne_f32_e32 v76, v76
	v_rndne_f32_e32 v77, v77
	v_fmac_f32_e32 v60, 0xc0c90fdb, v68
	v_fmac_f32_e32 v61, 0xc0c90fdb, v69
	v_fmac_f32_e32 v62, 0xc0c90fdb, v70
	v_fmac_f32_e32 v63, 0xc0c90fdb, v71
	v_fmac_f32_e32 v64, 0xc0c90fdb, v72
	v_fmac_f32_e32 v65, 0xc0c90fdb, v73
	v_fmac_f32_e32 v66, 0xc0c90fdb, v76
	v_fmac_f32_e32 v67, 0xc0c90fdb, v77
	v_fmac_f32_e32 v60, 0x343bbd2e, v68
	v_fmac_f32_e32 v61, 0x343bbd2e, v69
	v_fmac_f32_e32 v62, 0x343bbd2e, v70
	v_fmac_f32_e32 v63, 0x343bbd2e, v71
	v_fmac_f32_e32 v64, 0x343bbd2e, v72
	v_fmac_f32_e32 v65, 0x343bbd2e, v73
	v_fmac_f32_e32 v66, 0x343bbd2e, v76
	v_fmac_f32_e32 v67, 0x343bbd2e, v77
	v_mul_f32_e32 v60, 0.15915494, v60
	v_mul_f32_e32 v61, 0.15915494, v61
	v_mul_f32_e32 v62, 0.15915494, v62
	v_mul_f32_e32 v63, 0.15915494, v63
	v_mul_f32_e32 v64, 0.15915494, v64
	v_mul_f32_e32 v65, 0.15915494, v65
	v_mul_f32_e32 v66, 0.15915494, v66
	v_mul_f32_e32 v67, 0.15915494, v67
	v_sin_f32_e32 v68, v60
	v_sin_f32_e32 v69, v61
	v_sin_f32_e32 v70, v62
	v_sin_f32_e32 v71, v63
	v_sin_f32_e32 v72, v64
	v_sin_f32_e32 v73, v65
	v_sin_f32_e32 v76, v66
	v_sin_f32_e32 v77, v67
	v_cos_f32_e32 v60, v60
	v_cos_f32_e32 v61, v61
	v_cos_f32_e32 v62, v62
	v_cos_f32_e32 v63, v63
	v_cos_f32_e32 v64, v64
	v_cos_f32_e32 v65, v65
	v_cos_f32_e32 v66, v66
	v_cos_f32_e32 v67, v67
	s_nop 0
	v_mul_f32_e32 v171, v68, v34
	v_mul_f32_e32 v172, v60, v34
	v_fmac_f32_e32 v172, v68, v24
	v_fma_f32 v24, v60, v24, -v171
	v_mov_b32_e32 v34, v172
	v_mul_f32_e32 v171, v69, v35
	v_mul_f32_e32 v172, v61, v35
	v_fmac_f32_e32 v172, v69, v25
	v_fma_f32 v25, v61, v25, -v171
	v_mov_b32_e32 v35, v172
	v_mul_f32_e32 v171, v70, v36
	v_mul_f32_e32 v172, v62, v36
	v_fmac_f32_e32 v172, v70, v26
	v_fma_f32 v26, v62, v26, -v171
	v_mov_b32_e32 v36, v172
	v_mul_f32_e32 v171, v71, v37
	v_mul_f32_e32 v172, v63, v37
	v_fmac_f32_e32 v172, v71, v27
	v_fma_f32 v27, v63, v27, -v171
	v_mov_b32_e32 v37, v172
	v_mul_f32_e32 v171, v72, v38
	v_mul_f32_e32 v172, v64, v38
	v_fmac_f32_e32 v172, v72, v28
	v_fma_f32 v28, v64, v28, -v171
	v_mov_b32_e32 v38, v172
	v_mul_f32_e32 v171, v73, v39
	v_mul_f32_e32 v172, v65, v39
	v_fmac_f32_e32 v172, v73, v29
	v_fma_f32 v29, v65, v29, -v171
	v_mov_b32_e32 v39, v172
	v_mul_f32_e32 v171, v76, v40
	v_mul_f32_e32 v172, v66, v40
	v_fmac_f32_e32 v172, v76, v30
	v_fma_f32 v30, v66, v30, -v171
	v_mov_b32_e32 v40, v172
	v_mul_f32_e32 v171, v77, v41
	v_mul_f32_e32 v172, v67, v41
	v_fmac_f32_e32 v172, v77, v31
	v_fma_f32 v31, v67, v31, -v171
	v_mov_b32_e32 v41, v172
	v_cvt_pk_bf16_f32 v114, v24, v25
	v_cvt_pk_bf16_f32 v115, v26, v27
	v_cvt_pk_bf16_f32 v116, v28, v29
	v_cvt_pk_bf16_f32 v117, v30, v31
	v_cvt_pk_bf16_f32 v122, v34, v35
	v_cvt_pk_bf16_f32 v123, v36, v37
	v_cvt_pk_bf16_f32 v124, v38, v39
	v_cvt_pk_bf16_f32 v125, v40, v41
	v_lshlrev_b32_e32 v24, 16, v110
	v_and_b32_e32 v25, 0xffff0000, v110
	v_lshlrev_b32_e32 v26, 16, v111
	v_and_b32_e32 v27, 0xffff0000, v111
	v_lshlrev_b32_e32 v28, 16, v112
	v_and_b32_e32 v29, 0xffff0000, v112
	v_lshlrev_b32_e32 v30, 16, v113
	v_and_b32_e32 v31, 0xffff0000, v113
	v_lshlrev_b32_e32 v34, 16, v102
	v_and_b32_e32 v35, 0xffff0000, v102
	v_lshlrev_b32_e32 v36, 16, v103
	v_and_b32_e32 v37, 0xffff0000, v103
	v_lshlrev_b32_e32 v38, 16, v104
	v_and_b32_e32 v39, 0xffff0000, v104
	v_lshlrev_b32_e32 v40, 16, v105
	v_and_b32_e32 v41, 0xffff0000, v105
	v_mul_f32_e32 v24, v24, v169
	v_mul_f32_e32 v25, v25, v169
	v_mul_f32_e32 v26, v26, v169
	v_mul_f32_e32 v27, v27, v169
	v_mul_f32_e32 v28, v28, v169
	v_mul_f32_e32 v29, v29, v169
	v_mul_f32_e32 v30, v30, v169
	v_mul_f32_e32 v31, v31, v169
	v_mul_f32_e32 v24, v24, v224
	v_mul_f32_e32 v25, v25, v225
	v_mul_f32_e32 v26, v26, v226
	v_mul_f32_e32 v27, v27, v227
	v_mul_f32_e32 v28, v28, v228
	v_mul_f32_e32 v29, v29, v229
	v_mul_f32_e32 v30, v30, v230
	v_mul_f32_e32 v31, v31, v231
	v_mul_f32_e32 v34, v34, v169
	v_mul_f32_e32 v35, v35, v169
	v_mul_f32_e32 v36, v36, v169
	v_mul_f32_e32 v37, v37, v169
	v_mul_f32_e32 v38, v38, v169
	v_mul_f32_e32 v39, v39, v169
	v_mul_f32_e32 v40, v40, v169
	v_mul_f32_e32 v41, v41, v169
	v_mul_f32_e32 v34, v34, v240
	v_mul_f32_e32 v35, v35, v241
	v_mul_f32_e32 v36, v36, v242
	v_mul_f32_e32 v37, v37, v243
	v_mul_f32_e32 v38, v38, v244
	v_mul_f32_e32 v39, v39, v245
	v_mul_f32_e32 v40, v40, v246
	v_mul_f32_e32 v41, v41, v247
	v_mul_f32_e32 v60, v78, v95
	v_mul_f32_e32 v61, v79, v95
	v_mul_f32_e32 v62, v80, v95
	v_mul_f32_e32 v63, v81, v95
	v_mul_f32_e32 v64, v82, v95
	v_mul_f32_e32 v65, v83, v95
	v_mul_f32_e32 v66, v84, v95
	v_mul_f32_e32 v67, v85, v95
	v_mul_f32_e32 v68, 0.15915494, v60
	v_mul_f32_e32 v69, 0.15915494, v61
	v_mul_f32_e32 v70, 0.15915494, v62
	v_mul_f32_e32 v71, 0.15915494, v63
	v_mul_f32_e32 v72, 0.15915494, v64
	v_mul_f32_e32 v73, 0.15915494, v65
	v_mul_f32_e32 v76, 0.15915494, v66
	v_mul_f32_e32 v77, 0.15915494, v67
	v_rndne_f32_e32 v68, v68
	v_rndne_f32_e32 v69, v69
	v_rndne_f32_e32 v70, v70
	v_rndne_f32_e32 v71, v71
	v_rndne_f32_e32 v72, v72
	v_rndne_f32_e32 v73, v73
	v_rndne_f32_e32 v76, v76
	v_rndne_f32_e32 v77, v77
	v_fmac_f32_e32 v60, 0xc0c90fdb, v68
	v_fmac_f32_e32 v61, 0xc0c90fdb, v69
	v_fmac_f32_e32 v62, 0xc0c90fdb, v70
	v_fmac_f32_e32 v63, 0xc0c90fdb, v71
	v_fmac_f32_e32 v64, 0xc0c90fdb, v72
	v_fmac_f32_e32 v65, 0xc0c90fdb, v73
	v_fmac_f32_e32 v66, 0xc0c90fdb, v76
	v_fmac_f32_e32 v67, 0xc0c90fdb, v77
	v_fmac_f32_e32 v60, 0x343bbd2e, v68
	v_fmac_f32_e32 v61, 0x343bbd2e, v69
	v_fmac_f32_e32 v62, 0x343bbd2e, v70
	v_fmac_f32_e32 v63, 0x343bbd2e, v71
	v_fmac_f32_e32 v64, 0x343bbd2e, v72
	v_fmac_f32_e32 v65, 0x343bbd2e, v73
	v_fmac_f32_e32 v66, 0x343bbd2e, v76
	v_fmac_f32_e32 v67, 0x343bbd2e, v77
	v_mul_f32_e32 v60, 0.15915494, v60
	v_mul_f32_e32 v61, 0.15915494, v61
	v_mul_f32_e32 v62, 0.15915494, v62
	v_mul_f32_e32 v63, 0.15915494, v63
	v_mul_f32_e32 v64, 0.15915494, v64
	v_mul_f32_e32 v65, 0.15915494, v65
	v_mul_f32_e32 v66, 0.15915494, v66
	v_mul_f32_e32 v67, 0.15915494, v67
	v_sin_f32_e32 v68, v60
	v_sin_f32_e32 v69, v61
	v_sin_f32_e32 v70, v62
	v_sin_f32_e32 v71, v63
	v_sin_f32_e32 v72, v64
	v_sin_f32_e32 v73, v65
	v_sin_f32_e32 v76, v66
	v_sin_f32_e32 v77, v67
	v_cos_f32_e32 v60, v60
	v_cos_f32_e32 v61, v61
	v_cos_f32_e32 v62, v62
	v_cos_f32_e32 v63, v63
	v_cos_f32_e32 v64, v64
	v_cos_f32_e32 v65, v65
	v_cos_f32_e32 v66, v66
	v_cos_f32_e32 v67, v67
	s_nop 0
	v_mul_f32_e32 v171, v68, v34
	v_mul_f32_e32 v172, v60, v34
	v_fmac_f32_e32 v172, v68, v24
	v_fma_f32 v24, v60, v24, -v171
	v_mov_b32_e32 v34, v172
	v_mul_f32_e32 v171, v69, v35
	v_mul_f32_e32 v172, v61, v35
	v_fmac_f32_e32 v172, v69, v25
	v_fma_f32 v25, v61, v25, -v171
	v_mov_b32_e32 v35, v172
	v_mul_f32_e32 v171, v70, v36
	v_mul_f32_e32 v172, v62, v36
	v_fmac_f32_e32 v172, v70, v26
	v_fma_f32 v26, v62, v26, -v171
	v_mov_b32_e32 v36, v172
	v_mul_f32_e32 v171, v71, v37
	v_mul_f32_e32 v172, v63, v37
	v_fmac_f32_e32 v172, v71, v27
	v_fma_f32 v27, v63, v27, -v171
	v_mov_b32_e32 v37, v172
	v_mul_f32_e32 v171, v72, v38
	v_mul_f32_e32 v172, v64, v38
	v_fmac_f32_e32 v172, v72, v28
	v_fma_f32 v28, v64, v28, -v171
	v_mov_b32_e32 v38, v172
	v_mul_f32_e32 v171, v73, v39
	v_mul_f32_e32 v172, v65, v39
	v_fmac_f32_e32 v172, v73, v29
	v_fma_f32 v29, v65, v29, -v171
	v_mov_b32_e32 v39, v172
	v_mul_f32_e32 v171, v76, v40
	v_mul_f32_e32 v172, v66, v40
	v_fmac_f32_e32 v172, v76, v30
	v_fma_f32 v30, v66, v30, -v171
	v_mov_b32_e32 v40, v172
	v_mul_f32_e32 v171, v77, v41
	v_mul_f32_e32 v172, v67, v41
	v_fmac_f32_e32 v172, v77, v31
	v_fma_f32 v31, v67, v31, -v171
	v_mov_b32_e32 v41, v172
	v_cvt_pk_bf16_f32 v110, v24, v25
	v_cvt_pk_bf16_f32 v111, v26, v27
	v_cvt_pk_bf16_f32 v112, v28, v29
	v_cvt_pk_bf16_f32 v113, v30, v31
	v_cvt_pk_bf16_f32 v102, v34, v35
	v_cvt_pk_bf16_f32 v103, v36, v37
	v_cvt_pk_bf16_f32 v104, v38, v39
	v_cvt_pk_bf16_f32 v105, v40, v41
	v_lshlrev_b32_e32 v24, 16, v106
	v_and_b32_e32 v25, 0xffff0000, v106
	v_lshlrev_b32_e32 v26, 16, v107
	v_and_b32_e32 v27, 0xffff0000, v107
	v_lshlrev_b32_e32 v28, 16, v108
	v_and_b32_e32 v29, 0xffff0000, v108
	v_lshlrev_b32_e32 v30, 16, v109
	v_and_b32_e32 v31, 0xffff0000, v109
	v_lshlrev_b32_e32 v34, 16, v98
	v_and_b32_e32 v35, 0xffff0000, v98
	v_lshlrev_b32_e32 v36, 16, v99
	v_and_b32_e32 v37, 0xffff0000, v99
	v_lshlrev_b32_e32 v38, 16, v100
	v_and_b32_e32 v39, 0xffff0000, v100
	v_lshlrev_b32_e32 v40, 16, v101
	v_and_b32_e32 v41, 0xffff0000, v101
	v_mul_f32_e32 v24, v24, v169
	v_mul_f32_e32 v25, v25, v169
	v_mul_f32_e32 v26, v26, v169
	v_mul_f32_e32 v27, v27, v169
	v_mul_f32_e32 v28, v28, v169
	v_mul_f32_e32 v29, v29, v169
	v_mul_f32_e32 v30, v30, v169
	v_mul_f32_e32 v31, v31, v169
	v_mul_f32_e32 v24, v24, v232
	v_mul_f32_e32 v25, v25, v233
	v_mul_f32_e32 v26, v26, v234
	v_mul_f32_e32 v27, v27, v235
	v_mul_f32_e32 v28, v28, v236
	v_mul_f32_e32 v29, v29, v237
	v_mul_f32_e32 v30, v30, v238
	v_mul_f32_e32 v31, v31, v239
	v_mul_f32_e32 v34, v34, v169
	v_mul_f32_e32 v35, v35, v169
	v_mul_f32_e32 v36, v36, v169
	v_mul_f32_e32 v37, v37, v169
	v_mul_f32_e32 v38, v38, v169
	v_mul_f32_e32 v39, v39, v169
	v_mul_f32_e32 v40, v40, v169
	v_mul_f32_e32 v41, v41, v169
	v_mul_f32_e32 v34, v34, v248
	v_mul_f32_e32 v35, v35, v249
	v_mul_f32_e32 v36, v36, v250
	v_mul_f32_e32 v37, v37, v251
	v_mul_f32_e32 v38, v38, v164
	v_mul_f32_e32 v39, v39, v165
	v_mul_f32_e32 v40, v40, v166
	v_mul_f32_e32 v41, v41, v167
	v_mul_f32_e32 v60, v86, v95
	v_mul_f32_e32 v61, v87, v95
	v_mul_f32_e32 v62, v88, v95
	v_mul_f32_e32 v63, v89, v95
	v_mul_f32_e32 v64, v90, v95
	v_mul_f32_e32 v65, v91, v95
	v_mul_f32_e32 v66, v92, v95
	v_mul_f32_e32 v67, v93, v95
	v_mul_f32_e32 v68, 0.15915494, v60
	v_mul_f32_e32 v69, 0.15915494, v61
	v_mul_f32_e32 v70, 0.15915494, v62
	v_mul_f32_e32 v71, 0.15915494, v63
	v_mul_f32_e32 v72, 0.15915494, v64
	v_mul_f32_e32 v73, 0.15915494, v65
	v_mul_f32_e32 v76, 0.15915494, v66
	v_mul_f32_e32 v77, 0.15915494, v67
	v_rndne_f32_e32 v68, v68
	v_rndne_f32_e32 v69, v69
	v_rndne_f32_e32 v70, v70
	v_rndne_f32_e32 v71, v71
	v_rndne_f32_e32 v72, v72
	v_rndne_f32_e32 v73, v73
	v_rndne_f32_e32 v76, v76
	v_rndne_f32_e32 v77, v77
	v_fmac_f32_e32 v60, 0xc0c90fdb, v68
	v_fmac_f32_e32 v61, 0xc0c90fdb, v69
	v_fmac_f32_e32 v62, 0xc0c90fdb, v70
	v_fmac_f32_e32 v63, 0xc0c90fdb, v71
	v_fmac_f32_e32 v64, 0xc0c90fdb, v72
	v_fmac_f32_e32 v65, 0xc0c90fdb, v73
	v_fmac_f32_e32 v66, 0xc0c90fdb, v76
	v_fmac_f32_e32 v67, 0xc0c90fdb, v77
	v_fmac_f32_e32 v60, 0x343bbd2e, v68
	v_fmac_f32_e32 v61, 0x343bbd2e, v69
	v_fmac_f32_e32 v62, 0x343bbd2e, v70
	v_fmac_f32_e32 v63, 0x343bbd2e, v71
	v_fmac_f32_e32 v64, 0x343bbd2e, v72
	v_fmac_f32_e32 v65, 0x343bbd2e, v73
	v_fmac_f32_e32 v66, 0x343bbd2e, v76
	v_fmac_f32_e32 v67, 0x343bbd2e, v77
	v_mul_f32_e32 v60, 0.15915494, v60
	v_mul_f32_e32 v61, 0.15915494, v61
	v_mul_f32_e32 v62, 0.15915494, v62
	v_mul_f32_e32 v63, 0.15915494, v63
	v_mul_f32_e32 v64, 0.15915494, v64
	v_mul_f32_e32 v65, 0.15915494, v65
	v_mul_f32_e32 v66, 0.15915494, v66
	v_mul_f32_e32 v67, 0.15915494, v67
	v_sin_f32_e32 v68, v60
	v_sin_f32_e32 v69, v61
	v_sin_f32_e32 v70, v62
	v_sin_f32_e32 v71, v63
	v_sin_f32_e32 v72, v64
	v_sin_f32_e32 v73, v65
	v_sin_f32_e32 v76, v66
	v_sin_f32_e32 v77, v67
	v_cos_f32_e32 v60, v60
	v_cos_f32_e32 v61, v61
	v_cos_f32_e32 v62, v62
	v_cos_f32_e32 v63, v63
	v_cos_f32_e32 v64, v64
	v_cos_f32_e32 v65, v65
	v_cos_f32_e32 v66, v66
	v_cos_f32_e32 v67, v67
	s_nop 0
	v_mul_f32_e32 v171, v68, v34
	v_mul_f32_e32 v172, v60, v34
	v_fmac_f32_e32 v172, v68, v24
	v_fma_f32 v24, v60, v24, -v171
	v_mov_b32_e32 v34, v172
	v_mul_f32_e32 v171, v69, v35
	v_mul_f32_e32 v172, v61, v35
	v_fmac_f32_e32 v172, v69, v25
	v_fma_f32 v25, v61, v25, -v171
	v_mov_b32_e32 v35, v172
	v_mul_f32_e32 v171, v70, v36
	v_mul_f32_e32 v172, v62, v36
	v_fmac_f32_e32 v172, v70, v26
	v_fma_f32 v26, v62, v26, -v171
	v_mov_b32_e32 v36, v172
	v_mul_f32_e32 v171, v71, v37
	v_mul_f32_e32 v172, v63, v37
	v_fmac_f32_e32 v172, v71, v27
	v_fma_f32 v27, v63, v27, -v171
	v_mov_b32_e32 v37, v172
	v_mul_f32_e32 v171, v72, v38
	v_mul_f32_e32 v172, v64, v38
	v_fmac_f32_e32 v172, v72, v28
	v_fma_f32 v28, v64, v28, -v171
	v_mov_b32_e32 v38, v172
	v_mul_f32_e32 v171, v73, v39
	v_mul_f32_e32 v172, v65, v39
	v_fmac_f32_e32 v172, v73, v29
	v_fma_f32 v29, v65, v29, -v171
	v_mov_b32_e32 v39, v172
	v_mul_f32_e32 v171, v76, v40
	v_mul_f32_e32 v172, v66, v40
	v_fmac_f32_e32 v172, v76, v30
	v_fma_f32 v30, v66, v30, -v171
	v_mov_b32_e32 v40, v172
	v_mul_f32_e32 v171, v77, v41
	v_mul_f32_e32 v172, v67, v41
	v_fmac_f32_e32 v172, v77, v31
	v_fma_f32 v31, v67, v31, -v171
	v_mov_b32_e32 v41, v172
	v_cvt_pk_bf16_f32 v106, v24, v25
	v_cvt_pk_bf16_f32 v107, v26, v27
	v_cvt_pk_bf16_f32 v108, v28, v29
	v_cvt_pk_bf16_f32 v109, v30, v31
	v_cvt_pk_bf16_f32 v98, v34, v35
	v_cvt_pk_bf16_f32 v99, v36, v37
	v_cvt_pk_bf16_f32 v100, v38, v39
	v_cvt_pk_bf16_f32 v101, v40, v41
	v_lshlrev_b32_e32 v12, 8, v187
	v_and_b32_e32 v13, 0xf0, v53
	v_bitop3_b32 v0, v96, v12, v13 bitop3:0xde
	v_add_u32_e32 v196, 0, v0
	s_waitcnt lgkmcnt(0)
	s_barrier
	ds_read_b128 v[0:3], v196 offset:32768
	ds_read_b128 v[4:7], v196 offset:40960
	s_waitcnt vmcnt(7) lgkmcnt(1)
	v_mfma_f32_32x32x16_bf16 v[16:31], v[0:3], v[118:121], 0
	v_or_b32_e32 v0, 32, v96
	v_bitop3_b32 v0, v0, v12, v13 bitop3:0xde
	v_add_u32_e32 v201, 0, v0
	v_and_b32_e32 v15, 0xc0, v53
	v_lshlrev_b32_e32 v14, 3, v75
	s_mov_b32 s72, s73
	s_mov_b32 s74, s73
	s_waitcnt lgkmcnt(0)
	v_mfma_f32_32x32x16_bf16 v[32:47], v[4:7], v[118:121], 0
	ds_read_b128 v[0:3], v201 offset:32768
	ds_read_b128 v[4:7], v201 offset:40960
	s_mov_b32 s75, s73
	s_mov_b32 s76, s73
	s_mov_b32 s77, s73
	s_mov_b32 s78, s73
	s_mov_b32 s79, s73
	s_mov_b32 s80, s73
	s_waitcnt vmcnt(6) lgkmcnt(1)
	v_mfma_f32_32x32x16_bf16 v[16:31], v[0:3], v[114:117], v[16:31]
	v_or_b32_e32 v0, 64, v96
	v_bitop3_b32 v0, v0, v12, v13 bitop3:0xde
	v_add_u32_e32 v200, 0, v0
	s_mov_b32 s81, s73
	s_mov_b32 s82, s73
	s_mov_b32 s83, s73
	s_mov_b32 s84, s73
	s_waitcnt lgkmcnt(0)
	v_mfma_f32_32x32x16_bf16 v[32:47], v[4:7], v[114:117], v[32:47]
	ds_read_b128 v[0:3], v200 offset:32768
	ds_read_b128 v[4:7], v200 offset:40960
	s_mov_b32 s85, s73
	s_mov_b32 s86, s73
	s_mov_b32 s87, s73
	v_mov_b32_e32 v222, 9
	s_mov_b32 s3, 1
	v_mov_b32_e32 v189, 0
	s_waitcnt vmcnt(5) lgkmcnt(1)
	v_mfma_f32_32x32x16_bf16 v[16:31], v[0:3], v[126:129], v[16:31]
	v_or_b32_e32 v0, 0x60, v96
	v_bitop3_b32 v0, v0, v12, v13 bitop3:0xde
	v_add_u32_e32 v199, 0, v0
	s_waitcnt lgkmcnt(0)
	v_mfma_f32_32x32x16_bf16 v[32:47], v[4:7], v[126:129], v[32:47]
	ds_read_b128 v[0:3], v199 offset:32768
	ds_read_b128 v[4:7], v199 offset:40960
	s_waitcnt vmcnt(4) lgkmcnt(1)
	v_mfma_f32_32x32x16_bf16 v[16:31], v[0:3], v[122:125], v[16:31]
	v_or_b32_e32 v0, 0x80, v96
	v_bitop3_b32 v0, v0, v12, v13 bitop3:0xde
	v_add_u32_e32 v198, 0, v0
	s_waitcnt lgkmcnt(0)
	v_mfma_f32_32x32x16_bf16 v[32:47], v[4:7], v[122:125], v[32:47]
	ds_read_b128 v[0:3], v198 offset:32768
	ds_read_b128 v[4:7], v198 offset:40960
	s_waitcnt vmcnt(3) lgkmcnt(1)
	v_mfma_f32_32x32x16_bf16 v[16:31], v[0:3], v[110:113], v[16:31]
	v_or_b32_e32 v0, 0xa0, v96
	v_bitop3_b32 v0, v0, v12, v13 bitop3:0xde
	v_add_u32_e32 v197, 0, v0
	ds_read_b128 v[0:3], v197 offset:32768
	s_waitcnt lgkmcnt(1)
	v_mfma_f32_32x32x16_bf16 v[32:47], v[4:7], v[110:113], v[32:47]
	v_and_b32_e32 v4, 0x3fffffc0, v74
	v_lshl_add_u32 v183, v4, 2, s5
	ds_read_b128 v[4:7], v197 offset:40960
	s_cselect_b32 s5, 0, 0
	v_lshl_add_u32 v188, v187, 2, v183
	s_waitcnt vmcnt(2) lgkmcnt(1)
	v_mfma_f32_32x32x16_bf16 v[16:31], v[0:3], v[106:109], v[16:31]
	v_lshl_add_u64 v[0:1], v[50:51], 0, s[10:11]
	s_mov_b64 s[10:11], 0x6000
	v_lshl_add_u64 v[2:3], s[40:41], 0, v[0:1]
	v_lshl_add_u64 v[8:9], v[50:51], 0, s[10:11]
	v_lshl_add_u64 v[0:1], s[48:49], 0, v[0:1]
	v_lshl_add_u64 v[10:11], s[40:41], 0, v[8:9]
	global_load_dwordx4 v[52:55], v[2:3], off
	global_load_dwordx4 v[56:59], v[10:11], off
	v_lshl_add_u64 v[2:3], s[48:49], 0, v[8:9]
	global_load_dwordx4 v[60:63], v[0:1], off
	global_load_dwordx4 v[64:67], v[2:3], off
	v_or_b32_e32 v0, 0xc0, v96
	v_bitop3_b32 v0, v0, v12, v13 bitop3:0xde
	v_add_u32_e32 v203, 0, v0
	ds_read_b128 v[0:3], v203 offset:32768
	v_lshlrev_b32_e32 v9, 1, v74
	v_and_or_b32 v8, v14, 24, v15
	s_waitcnt lgkmcnt(1)
	v_mfma_f32_32x32x16_bf16 v[32:47], v[4:7], v[106:109], v[32:47]
	v_and_b32_e32 v4, 32, v9
	v_and_b32_e32 v5, 0x100, v14
	v_or3_b32 v76, v8, v4, v5
	ds_read_b128 v[4:7], v203 offset:40960
	s_mov_b64 s[10:11], 0xa000
	v_add_u32_e32 v191, s5, v76
	s_waitcnt vmcnt(5) lgkmcnt(1)
	v_mfma_f32_32x32x16_bf16 v[16:31], v[0:3], v[102:105], v[16:31]
	v_or_b32_e32 v0, 0xe0, v96
	v_bitop3_b32 v0, v0, v12, v13 bitop3:0xde
	v_add_u32_e32 v202, 0, v0
	ds_read_b128 v[0:3], v202 offset:32768
	ds_read_b128 v[68:71], v202 offset:40960
	s_waitcnt lgkmcnt(2)
	v_mfma_f32_32x32x16_bf16 v[32:47], v[4:7], v[102:105], v[32:47]
	s_waitcnt vmcnt(4) lgkmcnt(1)
	v_mfma_f32_32x32x16_bf16 v[16:31], v[0:3], v[98:101], v[16:31]
	v_mov_b64_e32 v[0:1], s[72:73]
	v_mov_b64_e32 v[14:15], s[86:87]
	v_mov_b64_e32 v[2:3], s[74:75]
	v_mov_b64_e32 v[4:5], s[76:77]
	v_mov_b64_e32 v[6:7], s[78:79]
	v_mov_b64_e32 v[8:9], s[80:81]
	v_mov_b64_e32 v[10:11], s[82:83]
	s_waitcnt lgkmcnt(0)
	v_mfma_f32_32x32x16_bf16 v[32:47], v[68:71], v[98:101], v[32:47]
	s_nop 2
	v_max_f32_e32 v68, v17, v17
	v_max_f32_e32 v69, v16, v16
	v_max_f32_e32 v68, v69, v68
	v_max3_f32 v68, v68, v18, v19
	v_max3_f32 v68, v68, v20, v21
	v_max3_f32 v68, v68, v22, v23
	v_max3_f32 v68, v68, v24, v25
	v_max3_f32 v68, v68, v26, v27
	v_max3_f32 v68, v68, v28, v29
	v_max3_f32 v68, v68, v30, v31
	v_max3_f32 v68, v68, v32, v33
	v_max3_f32 v68, v68, v34, v35
	v_max3_f32 v68, v68, v36, v37
	v_max3_f32 v68, v68, v38, v39
	v_max3_f32 v68, v68, v40, v41
	v_max3_f32 v68, v68, v42, v43
	v_max3_f32 v68, v68, v44, v45
	v_max3_f32 v77, v68, v46, v47
	v_lshl_add_u64 v[68:69], v[50:51], 0, s[10:11]
	v_lshl_add_u64 v[70:71], s[48:49], 0, v[68:69]
	v_lshl_add_u64 v[50:51], v[50:51], 0, s[12:13]
	v_lshl_add_u64 v[68:69], s[40:41], 0, v[68:69]
	v_lshl_add_u64 v[72:73], s[48:49], 0, v[50:51]
	global_load_dwordx4 v[138:141], v[70:71], off
	global_load_dwordx4 v[130:133], v[72:73], off
	v_lshl_add_u64 v[50:51], s[40:41], 0, v[50:51]
	global_load_dwordx4 v[142:145], v[68:69], off
	global_load_dwordx4 v[134:137], v[50:51], off
	v_mov_b32_e32 v78, v77
	s_nop 1
	v_permlane32_swap_b32_e32 v77, v78
	v_max_f32_e32 v50, v78, v78
	v_max_f32_e32 v51, v77, v77
	v_max_f32_e32 v50, v51, v50
	v_add_f32_e32 v51, 0x7149f2ca, v50
	v_cmp_ge_f32_e32 vcc, s35, v51
	s_cmp_eq_u64 vcc, exec
	v_max_f32_e32 v50, 0xf149f2ca, v50
	s_cselect_b64 vcc, -1, 0
	v_cndmask_b32_e32 v170, v50, v206, vcc
	v_sub_f32_e32 v51, 0xf149f2ca, v50
	v_mul_f32_e32 v50, 0xbe0293ee, v170
	v_fmamk_f32 v16, v16, 0x3e0293ee, v50
	v_exp_f32_e32 v163, v16
	v_fmamk_f32 v16, v17, 0x3e0293ee, v50
	v_exp_f32_e32 v177, v16
	v_fmamk_f32 v16, v18, 0x3e0293ee, v50
	v_exp_f32_e32 v164, v16
	v_fmamk_f32 v16, v19, 0x3e0293ee, v50
	v_exp_f32_e32 v227, v16
	v_fmamk_f32 v16, v20, 0x3e0293ee, v50
	v_exp_f32_e32 v176, v16
	v_fmamk_f32 v16, v21, 0x3e0293ee, v50
	v_exp_f32_e32 v230, v16
	v_fmamk_f32 v16, v22, 0x3e0293ee, v50
	v_exp_f32_e32 v165, v16
	v_fmamk_f32 v16, v23, 0x3e0293ee, v50
	v_exp_f32_e32 v175, v16
	v_fmamk_f32 v16, v24, 0x3e0293ee, v50
	v_mul_f32_e32 v51, 0x3e0293ee, v51
	v_exp_f32_e32 v166, v16
	v_fmamk_f32 v16, v25, 0x3e0293ee, v50
	v_exp_f32_e32 v51, v51
	v_exp_f32_e32 v173, v16
	v_fmamk_f32 v16, v26, 0x3e0293ee, v50
	v_exp_f32_e32 v167, v16
	v_fmamk_f32 v16, v27, 0x3e0293ee, v50
	v_exp_f32_e32 v174, v16
	v_fmamk_f32 v16, v28, 0x3e0293ee, v50
	s_addk_i32 s5, 0x4000
	s_mul_i32 s10, s42, 0x220000
	v_exp_f32_e32 v168, v16
	v_fmamk_f32 v16, v29, 0x3e0293ee, v50
	v_add_u32_e32 v190, s5, v76
	s_mul_hi_i32 s5, s42, 0x220000
	s_add_u32 s4, s10, s4
	v_pk_fma_f32 v[146:147], v[46:47], s[14:15], v[50:51] op_sel_hi:[1,0,0]
	v_pk_fma_f32 v[152:153], v[44:45], s[14:15], v[50:51] op_sel_hi:[1,0,0]
	v_pk_fma_f32 v[156:157], v[42:43], s[14:15], v[50:51] op_sel_hi:[1,0,0]
	v_pk_fma_f32 v[148:149], v[40:41], s[14:15], v[50:51] op_sel_hi:[1,0,0]
	v_pk_fma_f32 v[150:151], v[38:39], s[14:15], v[50:51] op_sel_hi:[1,0,0]
	v_pk_fma_f32 v[154:155], v[36:37], s[14:15], v[50:51] op_sel_hi:[1,0,0]
	v_pk_fma_f32 v[158:159], v[34:35], s[14:15], v[50:51] op_sel_hi:[1,0,0]
	v_pk_fma_f32 v[160:161], v[32:33], s[14:15], v[50:51] op_sel_hi:[1,0,0]
	v_exp_f32_e32 v171, v16
	v_fmamk_f32 v16, v30, 0x3e0293ee, v50
	v_fmac_f32_e32 v50, 0x3e0293ee, v31
	s_addc_u32 s5, s5, 0
	v_exp_f32_e32 v169, v16
	v_exp_f32_e32 v172, v50
	v_lshl_add_u64 v[16:17], s[4:5], 0, v[48:49]
	v_and_b32_e32 v18, 15, v74
	s_waitcnt vmcnt(4)
	v_lshl_or_b32 v16, v18, 4, v16
	v_mov_b64_e32 v[12:13], s[84:85]
	s_waitcnt vmcnt(7)
	ds_write_b128 v192, v[52:55] offset:16384
	s_waitcnt vmcnt(6)
	ds_write_b128 v193, v[56:59] offset:16384
	s_waitcnt vmcnt(5)
	ds_write_b128 v194, v[60:63] offset:49152
	s_waitcnt vmcnt(4)
	ds_write_b128 v195, v[64:67] offset:49152
	v_cndmask_b32_e64 v223, v51, 1.0, vcc
	v_lshl_add_u64 v[184:185], s[46:47], 0, v[16:17]
	v_mov_b64_e32 v[62:63], v[14:15]
	v_mov_b64_e32 v[46:47], v[14:15]
	v_mov_b64_e32 v[30:31], v[14:15]
	v_cmp_gt_u32_e64 s[40:41], 32, v75
	v_mov_b64_e32 v[60:61], v[12:13]
	v_mov_b64_e32 v[58:59], v[10:11]
	v_mov_b64_e32 v[56:57], v[8:9]
	v_mov_b64_e32 v[54:55], v[6:7]
	v_mov_b64_e32 v[52:53], v[4:5]
	v_mov_b64_e32 v[50:51], v[2:3]
	v_mov_b64_e32 v[48:49], v[0:1]
	v_mov_b64_e32 v[44:45], v[12:13]
	v_mov_b64_e32 v[42:43], v[10:11]
	v_mov_b64_e32 v[40:41], v[8:9]
	v_mov_b64_e32 v[38:39], v[6:7]
	v_mov_b64_e32 v[36:37], v[4:5]
	v_mov_b64_e32 v[34:35], v[2:3]
	v_mov_b64_e32 v[32:33], v[0:1]
	v_mov_b64_e32 v[28:29], v[12:13]
	v_mov_b64_e32 v[26:27], v[10:11]
	v_mov_b64_e32 v[24:25], v[8:9]
	v_mov_b64_e32 v[22:23], v[6:7]
	v_mov_b64_e32 v[20:21], v[4:5]
	v_mov_b64_e32 v[18:19], v[2:3]
	v_mov_b64_e32 v[16:17], v[0:1]
	s_waitcnt lgkmcnt(0)
	s_barrier
